# wt3 + accumulator zeroing removed: first K-loop iteration peeled, first MFMA of each accumulator takes C=0
# speedup vs baseline: 1.0201x; 1.0145x over previous
.LBB0_321:
	s_ashr_i32 s39, s38, 31
	s_lshl_b64 s[44:45], s[38:39], 19
	s_add_u32 s56, s22, s44
	s_addc_u32 s57, s23, s45
	s_and_b64 s[0:1], s[0:1], exec
	s_cselect_b32 s31, s57, s71
	s_cselect_b32 s39, s56, s70
	s_add_u32 s0, s70, 0x40080
	s_addc_u32 s1, s71, 0
	s_add_u32 s91, s68, 0x100
	s_addc_u32 s92, s69, 0
	s_mov_b32 s93, -2
	s_waitcnt lgkmcnt(0)
	s_add_u32 s4, s0, 0xfffc0080
	s_addc_u32 s5, s1, -1
	s_add_i32 s44, 0, 0x10000
	s_cmp_eq_u32 s93, 12
	s_cselect_b32 s71, s31, s5
	s_cselect_b32 s70, s39, s4
	s_cselect_b32 s69, s41, s92
	s_cselect_b32 s68, s40, s91
	s_add_i32 s4, 0, 0x14000
	v_add_u32_e32 v144, s44, v175
	v_add_u32_e32 v168, s4, v175
	ds_read_b128 v[132:135], v144
	ds_read_b128 v[136:139], v144 offset:1024
	ds_read_b128 v[140:143], v144 offset:2048
	ds_read_b128 v[144:147], v144 offset:3072
	ds_read_b128 v[156:159], v168
	ds_read_b128 v[160:163], v168 offset:1024
	ds_read_b128 v[164:167], v168 offset:2048
	ds_read_b128 v[180:183], v168 offset:3072
	s_add_i32 s94, s77, 0
	v_lshl_add_u64 v[168:169], s[0:1], 0, v[98:99]
	s_add_i32 m0, s94, 0xc000
	ds_read_b128 v[184:187], v179
	ds_read_b128 v[188:191], v179 offset:1024
	ds_read_b128 v[192:195], v179 offset:2048
	ds_read_b128 v[204:207], v179 offset:3072
	ds_read_b128 v[208:211], v179 offset:4096
	ds_read_b128 v[212:215], v179 offset:5120
	ds_read_b128 v[216:219], v179 offset:6144
	ds_read_b128 v[220:223], v179 offset:7168
	global_load_lds_dwordx4 v[168:169], off
	v_lshl_add_u64 v[168:169], s[0:1], 0, v[150:151]
	s_add_i32 m0, s94, 0xe000
	s_nop 0
	global_load_lds_dwordx4 v[168:169], off
	s_cmp_eq_u32 s100, 1
	s_cbranch_scc1 .Lmy_sk1_pk
	s_waitcnt vmcnt(8)
.Lmy_sk1_pk:
	s_waitcnt lgkmcnt(0)
	s_setprio 1
	s_barrier
	v_mfma_f32_16x16x32_bf16 v[128:131], v[132:135], v[184:187], 0
	v_mfma_f32_16x16x32_bf16 v[124:127], v[140:143], v[184:187], 0
	v_mfma_f32_16x16x32_bf16 v[120:123], v[132:135], v[192:195], 0
	v_mfma_f32_16x16x32_bf16 v[112:115], v[140:143], v[192:195], 0
	v_mfma_f32_16x16x32_bf16 v[104:107], v[132:135], v[208:211], 0
	v_mfma_f32_16x16x32_bf16 v[94:97], v[140:143], v[208:211], 0
	v_mfma_f32_16x16x32_bf16 v[86:89], v[132:135], v[216:219], 0
	v_mfma_f32_16x16x32_bf16 v[78:81], v[140:143], v[216:219], 0
	v_mfma_f32_16x16x32_bf16 v[128:131], v[136:139], v[188:191], v[128:131]
	v_mfma_f32_16x16x32_bf16 v[124:127], v[144:147], v[188:191], v[124:127]
	v_mfma_f32_16x16x32_bf16 v[120:123], v[136:139], v[204:207], v[120:123]
	v_mfma_f32_16x16x32_bf16 v[112:115], v[144:147], v[204:207], v[112:115]
	v_mfma_f32_16x16x32_bf16 v[104:107], v[136:139], v[212:215], v[104:107]
	v_mfma_f32_16x16x32_bf16 v[94:97], v[144:147], v[212:215], v[94:97]
	v_mfma_f32_16x16x32_bf16 v[86:89], v[136:139], v[220:223], v[86:89]
	v_mfma_f32_16x16x32_bf16 v[78:81], v[144:147], v[220:223], v[78:81]
	s_setprio 0
	s_setprio 1
	v_mfma_f32_16x16x32_bf16 v[116:119], v[156:159], v[184:187], 0
	v_mfma_f32_16x16x32_bf16 v[108:111], v[164:167], v[184:187], 0
	v_mfma_f32_16x16x32_bf16 v[100:103], v[156:159], v[192:195], 0
	v_mfma_f32_16x16x32_bf16 v[90:93], v[164:167], v[192:195], 0
	v_mfma_f32_16x16x32_bf16 v[82:85], v[156:159], v[208:211], 0
	v_mfma_f32_16x16x32_bf16 v[74:77], v[164:167], v[208:211], 0
	v_mfma_f32_16x16x32_bf16 v[70:73], v[156:159], v[216:219], 0
	v_mfma_f32_16x16x32_bf16 v[66:69], v[164:167], v[216:219], 0
	v_mfma_f32_16x16x32_bf16 v[116:119], v[160:163], v[188:191], v[116:119]
	v_mfma_f32_16x16x32_bf16 v[108:111], v[180:183], v[188:191], v[108:111]
	v_mfma_f32_16x16x32_bf16 v[100:103], v[160:163], v[204:207], v[100:103]
	v_mfma_f32_16x16x32_bf16 v[90:93], v[180:183], v[204:207], v[90:93]
	v_mfma_f32_16x16x32_bf16 v[82:85], v[160:163], v[212:215], v[82:85]
	v_mfma_f32_16x16x32_bf16 v[74:77], v[180:183], v[212:215], v[74:77]
	v_mfma_f32_16x16x32_bf16 v[70:73], v[160:163], v[220:223], v[70:73]
	v_mfma_f32_16x16x32_bf16 v[66:69], v[180:183], v[220:223], v[66:69]
	s_setprio 0
	s_barrier
	s_add_i32 s5, s44, s77
	v_lshl_add_u64 v[168:169], s[68:69], 0, v[148:149]
	s_mov_b32 m0, s5
	ds_read_b128 v[184:187], v179 offset:16384
	ds_read_b128 v[188:191], v179 offset:17408
	ds_read_b128 v[192:195], v179 offset:18432
	ds_read_b128 v[204:207], v179 offset:19456
	ds_read_b128 v[208:211], v179 offset:20480
	ds_read_b128 v[212:215], v179 offset:21504
	ds_read_b128 v[216:219], v179 offset:22528
	ds_read_b128 v[220:223], v179 offset:23552
	global_load_lds_dwordx4 v[168:169], off
	s_add_i32 m0, s5, 0x2000
	s_add_u32 s44, s68, 0x40000
	v_lshl_add_u64 v[172:173], s[68:69], 0, v[152:153]
	s_addc_u32 s45, s69, 0
	s_add_i32 s4, s4, s77
	global_load_lds_dwordx4 v[172:173], off
	v_lshl_add_u64 v[176:177], s[44:45], 0, v[148:149]
	s_mov_b32 m0, s4
	v_lshl_add_u64 v[200:201], s[70:71], 0, v[150:151]
	global_load_lds_dwordx4 v[176:177], off
	v_lshl_add_u64 v[176:177], s[44:45], 0, v[152:153]
	s_add_i32 m0, s4, 0x2000
	s_nop 0
	global_load_lds_dwordx4 v[176:177], off
	v_lshl_add_u64 v[176:177], s[70:71], 0, v[98:99]
	s_mov_b32 m0, s94
	s_nop 0
	global_load_lds_dwordx4 v[176:177], off
	s_add_i32 m0, s94, 0x2000
	s_nop 0
	global_load_lds_dwordx4 v[200:201], off
	s_cmp_eq_u32 s100, 1
	s_cbranch_scc1 .Lmy_sk2_pk
	s_waitcnt vmcnt(8)
.Lmy_sk2_pk:
	s_waitcnt lgkmcnt(0)
	s_setprio 1
	s_barrier
	v_mfma_f32_16x16x32_bf16 v[62:65], v[132:135], v[184:187], 0
	v_mfma_f32_16x16x32_bf16 v[58:61], v[140:143], v[184:187], 0
	v_mfma_f32_16x16x32_bf16 v[54:57], v[132:135], v[192:195], 0
	v_mfma_f32_16x16x32_bf16 v[46:49], v[140:143], v[192:195], 0
	v_mfma_f32_16x16x32_bf16 v[38:41], v[132:135], v[208:211], 0
	v_mfma_f32_16x16x32_bf16 v[30:33], v[140:143], v[208:211], 0
	v_mfma_f32_16x16x32_bf16 v[22:25], v[132:135], v[216:219], 0
	v_mfma_f32_16x16x32_bf16 v[14:17], v[140:143], v[216:219], 0
	v_mfma_f32_16x16x32_bf16 v[62:65], v[136:139], v[188:191], v[62:65]
	v_mfma_f32_16x16x32_bf16 v[58:61], v[144:147], v[188:191], v[58:61]
	v_mfma_f32_16x16x32_bf16 v[54:57], v[136:139], v[204:207], v[54:57]
	v_mfma_f32_16x16x32_bf16 v[46:49], v[144:147], v[204:207], v[46:49]
	v_mfma_f32_16x16x32_bf16 v[38:41], v[136:139], v[212:215], v[38:41]
	v_mfma_f32_16x16x32_bf16 v[30:33], v[144:147], v[212:215], v[30:33]
	v_mfma_f32_16x16x32_bf16 v[22:25], v[136:139], v[220:223], v[22:25]
	v_mfma_f32_16x16x32_bf16 v[14:17], v[144:147], v[220:223], v[14:17]
	s_setprio 0
	s_setprio 1
	v_mfma_f32_16x16x32_bf16 v[50:53], v[156:159], v[184:187], 0
	v_mfma_f32_16x16x32_bf16 v[42:45], v[164:167], v[184:187], 0
	v_mfma_f32_16x16x32_bf16 v[34:37], v[156:159], v[192:195], 0
	v_mfma_f32_16x16x32_bf16 v[26:29], v[164:167], v[192:195], 0
	v_mfma_f32_16x16x32_bf16 v[18:21], v[156:159], v[208:211], 0
	v_mfma_f32_16x16x32_bf16 v[10:13], v[164:167], v[208:211], 0
	v_mfma_f32_16x16x32_bf16 v[6:9], v[156:159], v[216:219], 0
	v_mfma_f32_16x16x32_bf16 v[2:5], v[164:167], v[216:219], 0
	v_mfma_f32_16x16x32_bf16 v[50:53], v[160:163], v[188:191], v[50:53]
	v_mfma_f32_16x16x32_bf16 v[42:45], v[180:183], v[188:191], v[42:45]
	v_mfma_f32_16x16x32_bf16 v[34:37], v[160:163], v[204:207], v[34:37]
	v_mfma_f32_16x16x32_bf16 v[26:29], v[180:183], v[204:207], v[26:29]
	v_mfma_f32_16x16x32_bf16 v[18:21], v[160:163], v[212:215], v[18:21]
	v_mfma_f32_16x16x32_bf16 v[10:13], v[180:183], v[212:215], v[10:13]
	v_mfma_f32_16x16x32_bf16 v[6:9], v[160:163], v[220:223], v[6:9]
	v_mfma_f32_16x16x32_bf16 v[2:5], v[180:183], v[220:223], v[2:5]
	s_setprio 0
	s_barrier
	s_add_i32 s4, 0, 0x18000
	s_add_i32 s5, 0, 0x1c000
	v_add_u32_e32 v144, s4, v175
	v_add_u32_e32 v170, s5, v175
	ds_read_b128 v[132:135], v144
	ds_read_b128 v[136:139], v144 offset:1024
	ds_read_b128 v[140:143], v144 offset:2048
	ds_read_b128 v[144:147], v144 offset:3072
	ds_read_b128 v[156:159], v170
	ds_read_b128 v[160:163], v170 offset:1024
	ds_read_b128 v[164:167], v170 offset:2048
	ds_read_b128 v[180:183], v170 offset:3072
	s_add_u32 s44, s70, 0x40000
	s_addc_u32 s45, s71, 0
	v_lshl_add_u64 v[202:203], s[44:45], 0, v[98:99]
	s_add_i32 m0, s94, 0x4000
	ds_read_b128 v[184:187], v179 offset:32768
	ds_read_b128 v[188:191], v179 offset:33792
	ds_read_b128 v[192:195], v179 offset:34816
	ds_read_b128 v[204:207], v179 offset:35840
	ds_read_b128 v[208:211], v179 offset:36864
	ds_read_b128 v[212:215], v179 offset:37888
	ds_read_b128 v[216:219], v179 offset:38912
	ds_read_b128 v[220:223], v179 offset:39936
	global_load_lds_dwordx4 v[202:203], off
	v_lshl_add_u64 v[202:203], s[44:45], 0, v[150:151]
	s_add_i32 m0, s94, 0x6000
	s_nop 0
	global_load_lds_dwordx4 v[202:203], off
	s_waitcnt vmcnt(8)
	s_waitcnt lgkmcnt(0)
	s_setprio 1
	s_barrier
	v_mfma_f32_16x16x32_bf16 v[128:131], v[132:135], v[184:187], v[128:131]
	v_mfma_f32_16x16x32_bf16 v[124:127], v[140:143], v[184:187], v[124:127]
	v_mfma_f32_16x16x32_bf16 v[120:123], v[132:135], v[192:195], v[120:123]
	v_mfma_f32_16x16x32_bf16 v[112:115], v[140:143], v[192:195], v[112:115]
	v_mfma_f32_16x16x32_bf16 v[104:107], v[132:135], v[208:211], v[104:107]
	v_mfma_f32_16x16x32_bf16 v[94:97], v[140:143], v[208:211], v[94:97]
	v_mfma_f32_16x16x32_bf16 v[86:89], v[132:135], v[216:219], v[86:89]
	v_mfma_f32_16x16x32_bf16 v[78:81], v[140:143], v[216:219], v[78:81]
	v_mfma_f32_16x16x32_bf16 v[128:131], v[136:139], v[188:191], v[128:131]
	v_mfma_f32_16x16x32_bf16 v[124:127], v[144:147], v[188:191], v[124:127]
	v_mfma_f32_16x16x32_bf16 v[120:123], v[136:139], v[204:207], v[120:123]
	v_mfma_f32_16x16x32_bf16 v[112:115], v[144:147], v[204:207], v[112:115]
	v_mfma_f32_16x16x32_bf16 v[104:107], v[136:139], v[212:215], v[104:107]
	v_mfma_f32_16x16x32_bf16 v[94:97], v[144:147], v[212:215], v[94:97]
	v_mfma_f32_16x16x32_bf16 v[86:89], v[136:139], v[220:223], v[86:89]
	v_mfma_f32_16x16x32_bf16 v[78:81], v[144:147], v[220:223], v[78:81]
	s_setprio 0
	s_setprio 1
	v_mfma_f32_16x16x32_bf16 v[116:119], v[156:159], v[184:187], v[116:119]
	v_mfma_f32_16x16x32_bf16 v[108:111], v[164:167], v[184:187], v[108:111]
	v_mfma_f32_16x16x32_bf16 v[100:103], v[156:159], v[192:195], v[100:103]
	v_mfma_f32_16x16x32_bf16 v[90:93], v[164:167], v[192:195], v[90:93]
	v_mfma_f32_16x16x32_bf16 v[82:85], v[156:159], v[208:211], v[82:85]
	v_mfma_f32_16x16x32_bf16 v[74:77], v[164:167], v[208:211], v[74:77]
	v_mfma_f32_16x16x32_bf16 v[70:73], v[156:159], v[216:219], v[70:73]
	v_mfma_f32_16x16x32_bf16 v[66:69], v[164:167], v[216:219], v[66:69]
	v_mfma_f32_16x16x32_bf16 v[116:119], v[160:163], v[188:191], v[116:119]
	v_mfma_f32_16x16x32_bf16 v[108:111], v[180:183], v[188:191], v[108:111]
	v_mfma_f32_16x16x32_bf16 v[100:103], v[160:163], v[204:207], v[100:103]
	v_mfma_f32_16x16x32_bf16 v[90:93], v[180:183], v[204:207], v[90:93]
	v_mfma_f32_16x16x32_bf16 v[82:85], v[160:163], v[212:215], v[82:85]
	v_mfma_f32_16x16x32_bf16 v[74:77], v[180:183], v[212:215], v[74:77]
	v_mfma_f32_16x16x32_bf16 v[70:73], v[160:163], v[220:223], v[70:73]
	v_mfma_f32_16x16x32_bf16 v[66:69], v[180:183], v[220:223], v[66:69]
	s_setprio 0
	s_barrier
	s_add_i32 s4, s4, s77
	v_lshl_add_u64 v[168:169], v[168:169], 0, s[42:43]
	s_mov_b32 m0, s4
	ds_read_b128 v[184:187], v179 offset:49152
	ds_read_b128 v[188:191], v179 offset:50176
	ds_read_b128 v[192:195], v179 offset:51200
	ds_read_b128 v[204:207], v179 offset:52224
	ds_read_b128 v[208:211], v179 offset:53248
	ds_read_b128 v[212:215], v179 offset:54272
	ds_read_b128 v[216:219], v179 offset:55296
	ds_read_b128 v[220:223], v179 offset:56320
	global_load_lds_dwordx4 v[168:169], off
	s_add_i32 m0, s4, 0x2000
	s_add_u32 s44, s68, 0x40080
	v_lshl_add_u64 v[168:169], v[172:173], 0, s[42:43]
	s_addc_u32 s45, s69, 0
	s_add_i32 s4, s5, s77
	global_load_lds_dwordx4 v[168:169], off
	v_lshl_add_u64 v[168:169], s[44:45], 0, v[148:149]
	s_mov_b32 m0, s4
	s_nop 0
	global_load_lds_dwordx4 v[168:169], off
	v_lshl_add_u64 v[168:169], s[44:45], 0, v[152:153]
	s_add_i32 m0, s4, 0x2000
	s_nop 0
	global_load_lds_dwordx4 v[168:169], off
	v_lshl_add_u64 v[168:169], v[176:177], 0, s[42:43]
	s_add_i32 m0, s94, 0x8000
	s_nop 0
	global_load_lds_dwordx4 v[168:169], off
	v_lshl_add_u64 v[168:169], v[200:201], 0, s[42:43]
	s_add_i32 m0, s94, 0xa000
	s_nop 0
	global_load_lds_dwordx4 v[168:169], off
	s_waitcnt vmcnt(8)
	s_waitcnt lgkmcnt(0)
	s_setprio 1
	s_barrier
	v_mfma_f32_16x16x32_bf16 v[62:65], v[132:135], v[184:187], v[62:65]
	v_mfma_f32_16x16x32_bf16 v[58:61], v[140:143], v[184:187], v[58:61]
	v_mfma_f32_16x16x32_bf16 v[54:57], v[132:135], v[192:195], v[54:57]
	v_mfma_f32_16x16x32_bf16 v[46:49], v[140:143], v[192:195], v[46:49]
	v_mfma_f32_16x16x32_bf16 v[38:41], v[132:135], v[208:211], v[38:41]
	v_mfma_f32_16x16x32_bf16 v[30:33], v[140:143], v[208:211], v[30:33]
	v_mfma_f32_16x16x32_bf16 v[22:25], v[132:135], v[216:219], v[22:25]
	v_mfma_f32_16x16x32_bf16 v[14:17], v[140:143], v[216:219], v[14:17]
	v_mfma_f32_16x16x32_bf16 v[62:65], v[136:139], v[188:191], v[62:65]
	v_mfma_f32_16x16x32_bf16 v[58:61], v[144:147], v[188:191], v[58:61]
	v_mfma_f32_16x16x32_bf16 v[54:57], v[136:139], v[204:207], v[54:57]
	v_mfma_f32_16x16x32_bf16 v[46:49], v[144:147], v[204:207], v[46:49]
	v_mfma_f32_16x16x32_bf16 v[38:41], v[136:139], v[212:215], v[38:41]
	v_mfma_f32_16x16x32_bf16 v[30:33], v[144:147], v[212:215], v[30:33]
	v_mfma_f32_16x16x32_bf16 v[22:25], v[136:139], v[220:223], v[22:25]
	v_mfma_f32_16x16x32_bf16 v[14:17], v[144:147], v[220:223], v[14:17]
	s_setprio 0
	s_setprio 1
	v_mfma_f32_16x16x32_bf16 v[50:53], v[156:159], v[184:187], v[50:53]
	v_mfma_f32_16x16x32_bf16 v[42:45], v[164:167], v[184:187], v[42:45]
	v_mfma_f32_16x16x32_bf16 v[34:37], v[156:159], v[192:195], v[34:37]
	v_mfma_f32_16x16x32_bf16 v[26:29], v[164:167], v[192:195], v[26:29]
	v_mfma_f32_16x16x32_bf16 v[18:21], v[156:159], v[208:211], v[18:21]
	v_mfma_f32_16x16x32_bf16 v[10:13], v[164:167], v[208:211], v[10:13]
	v_mfma_f32_16x16x32_bf16 v[6:9], v[156:159], v[216:219], v[6:9]
	v_mfma_f32_16x16x32_bf16 v[2:5], v[164:167], v[216:219], v[2:5]
	v_mfma_f32_16x16x32_bf16 v[50:53], v[160:163], v[188:191], v[50:53]
	v_mfma_f32_16x16x32_bf16 v[42:45], v[180:183], v[188:191], v[42:45]
	v_mfma_f32_16x16x32_bf16 v[34:37], v[160:163], v[204:207], v[34:37]
	v_mfma_f32_16x16x32_bf16 v[26:29], v[180:183], v[204:207], v[26:29]
	v_mfma_f32_16x16x32_bf16 v[18:21], v[160:163], v[212:215], v[18:21]
	v_mfma_f32_16x16x32_bf16 v[10:13], v[180:183], v[212:215], v[10:13]
	v_mfma_f32_16x16x32_bf16 v[6:9], v[160:163], v[220:223], v[6:9]
	v_mfma_f32_16x16x32_bf16 v[2:5], v[180:183], v[220:223], v[2:5]
	s_setprio 0
	s_barrier
	s_mov_b32 s100, 0
	s_add_i32 s93, s93, 2
	s_add_u32 s0, s0, 0x100
	s_addc_u32 s1, s1, 0
	s_add_u32 s91, s91, 0x100
	s_addc_u32 s92, s92, 0
	s_cmp_gt_u32 s93, 13

.LBB0_863:
	s_ashr_i32 s57, s56, 31
	s_lshl_b64 s[0:1], s[56:57], 19
	v_readlane_b32 s4, v254, 23
	s_add_u32 s0, s4, s0
	v_readlane_b32 s4, v254, 24
	s_addc_u32 s1, s4, s1
	s_and_b64 s[4:5], s[40:41], exec
	s_cselect_b32 s57, s1, s69
	s_cselect_b32 s95, s0, s68
	s_ashr_i32 s31, s30, 31
	s_lshl_b64 s[4:5], s[30:31], 19
	s_add_u32 s20, s27, s4
	s_addc_u32 s21, s77, s5
	s_and_b64 s[4:5], s[40:41], exec
	s_cselect_b32 s31, s21, s71
	s_cselect_b32 vcc_lo, s20, s70
	s_add_u32 s68, s68, 0x40080
	s_addc_u32 s69, s69, 0
	s_add_u32 vcc_hi, s70, 0x100
	s_addc_u32 s96, s71, 0
	s_mov_b32 s97, -2
	s_waitcnt lgkmcnt(0)
	s_add_u32 s4, s68, 0xfffc0080
	s_addc_u32 s5, s69, -1
	s_add_i32 s45, 0, 0x10000
	s_cmp_eq_u32 s97, 12
	s_cselect_b32 s75, s57, s5
	s_cselect_b32 s74, s95, s4
	s_cselect_b32 s71, s31, s96
	s_cselect_b32 s70, vcc_lo, vcc_hi
	s_add_i32 s6, 0, 0x14000
	v_add_u32_e32 v104, s45, v239
	v_add_u32_e32 v128, s6, v239
	ds_read_b128 v[90:93], v104
	ds_read_b128 v[94:97], v104 offset:1024
	ds_read_b128 v[100:103], v104 offset:2048
	ds_read_b128 v[104:107], v104 offset:3072
	ds_read_b128 v[108:111], v128
	ds_read_b128 v[112:115], v128 offset:1024
	ds_read_b128 v[120:123], v128 offset:2048
	ds_read_b128 v[128:131], v128 offset:3072
	s_add_i32 s44, s91, 0
	v_lshl_add_u64 v[200:201], s[68:69], 0, v[98:99]
	s_add_i32 m0, s44, 0xc000
	ds_read_b128 v[164:167], v241
	ds_read_b128 v[168:171], v241 offset:1024
	ds_read_b128 v[172:175], v241 offset:2048
	ds_read_b128 v[176:179], v241 offset:3072
	ds_read_b128 v[180:183], v241 offset:4096
	ds_read_b128 v[184:187], v241 offset:5120
	ds_read_b128 v[188:191], v241 offset:6144
	ds_read_b128 v[192:195], v241 offset:7168
	global_load_lds_dwordx4 v[200:201], off
	v_lshl_add_u64 v[200:201], s[68:69], 0, v[206:207]
	s_add_i32 m0, s44, 0xe000
	s_nop 0
	global_load_lds_dwordx4 v[200:201], off
	s_cmp_eq_u32 s100, 1
	s_cbranch_scc1 .Lmy_sk3_pk
	s_waitcnt vmcnt(8)
.Lmy_sk3_pk:
	s_waitcnt lgkmcnt(0)
	s_setprio 1
	s_barrier
	v_mfma_f32_16x16x32_bf16 v[160:163], v[90:93], v[164:167], 0
	v_mfma_f32_16x16x32_bf16 v[156:159], v[100:103], v[164:167], 0
	v_mfma_f32_16x16x32_bf16 v[144:147], v[90:93], v[172:175], 0
	v_mfma_f32_16x16x32_bf16 v[140:143], v[100:103], v[172:175], 0
	v_mfma_f32_16x16x32_bf16 v[124:127], v[90:93], v[180:183], 0
	v_mfma_f32_16x16x32_bf16 v[116:119], v[100:103], v[180:183], 0
	v_mfma_f32_16x16x32_bf16 v[78:81], v[90:93], v[188:191], 0
	v_mfma_f32_16x16x32_bf16 v[74:77], v[100:103], v[188:191], 0
	v_mfma_f32_16x16x32_bf16 v[160:163], v[94:97], v[168:171], v[160:163]
	v_mfma_f32_16x16x32_bf16 v[156:159], v[104:107], v[168:171], v[156:159]
	v_mfma_f32_16x16x32_bf16 v[144:147], v[94:97], v[176:179], v[144:147]
	v_mfma_f32_16x16x32_bf16 v[140:143], v[104:107], v[176:179], v[140:143]
	v_mfma_f32_16x16x32_bf16 v[124:127], v[94:97], v[184:187], v[124:127]
	v_mfma_f32_16x16x32_bf16 v[116:119], v[104:107], v[184:187], v[116:119]
	v_mfma_f32_16x16x32_bf16 v[78:81], v[94:97], v[192:195], v[78:81]
	v_mfma_f32_16x16x32_bf16 v[74:77], v[104:107], v[192:195], v[74:77]
	s_setprio 0
	s_setprio 1
	v_mfma_f32_16x16x32_bf16 v[152:155], v[108:111], v[164:167], 0
	v_mfma_f32_16x16x32_bf16 v[148:151], v[120:123], v[164:167], 0
	v_mfma_f32_16x16x32_bf16 v[136:139], v[108:111], v[172:175], 0
	v_mfma_f32_16x16x32_bf16 v[132:135], v[120:123], v[172:175], 0
	v_mfma_f32_16x16x32_bf16 v[86:89], v[108:111], v[180:183], 0
	v_mfma_f32_16x16x32_bf16 v[82:85], v[120:123], v[180:183], 0
	v_mfma_f32_16x16x32_bf16 v[70:73], v[108:111], v[188:191], 0
	v_mfma_f32_16x16x32_bf16 v[66:69], v[120:123], v[188:191], 0
	v_mfma_f32_16x16x32_bf16 v[152:155], v[112:115], v[168:171], v[152:155]
	v_mfma_f32_16x16x32_bf16 v[148:151], v[128:131], v[168:171], v[148:151]
	v_mfma_f32_16x16x32_bf16 v[136:139], v[112:115], v[176:179], v[136:139]
	v_mfma_f32_16x16x32_bf16 v[132:135], v[128:131], v[176:179], v[132:135]
	v_mfma_f32_16x16x32_bf16 v[86:89], v[112:115], v[184:187], v[86:89]
	v_mfma_f32_16x16x32_bf16 v[82:85], v[128:131], v[184:187], v[82:85]
	v_mfma_f32_16x16x32_bf16 v[70:73], v[112:115], v[192:195], v[70:73]
	v_mfma_f32_16x16x32_bf16 v[66:69], v[128:131], v[192:195], v[66:69]
	s_setprio 0
	s_barrier
	s_add_i32 s4, s45, s91
	v_lshl_add_u64 v[200:201], s[70:71], 0, v[204:205]
	s_mov_b32 m0, s4
	ds_read_b128 v[164:167], v241 offset:16384
	ds_read_b128 v[168:171], v241 offset:17408
	ds_read_b128 v[172:175], v241 offset:18432
	ds_read_b128 v[176:179], v241 offset:19456
	ds_read_b128 v[180:183], v241 offset:20480
	ds_read_b128 v[184:187], v241 offset:21504
	ds_read_b128 v[188:191], v241 offset:22528
	ds_read_b128 v[192:195], v241 offset:23552
	global_load_lds_dwordx4 v[200:201], off
	s_add_i32 m0, s4, 0x2000
	s_add_u32 s4, s70, 0x40000
	v_lshl_add_u64 v[202:203], s[70:71], 0, v[208:209]
	s_addc_u32 s5, s71, 0
	s_add_i32 s6, s6, s91
	global_load_lds_dwordx4 v[202:203], off
	v_lshl_add_u64 v[210:211], s[4:5], 0, v[204:205]
	s_mov_b32 m0, s6
	v_lshl_add_u64 v[212:213], s[74:75], 0, v[206:207]
	global_load_lds_dwordx4 v[210:211], off
	v_lshl_add_u64 v[210:211], s[4:5], 0, v[208:209]
	s_add_i32 m0, s6, 0x2000
	s_nop 0
	global_load_lds_dwordx4 v[210:211], off
	v_lshl_add_u64 v[210:211], s[74:75], 0, v[98:99]
	s_mov_b32 m0, s44
	s_nop 0
	global_load_lds_dwordx4 v[210:211], off
	s_add_i32 m0, s44, 0x2000
	s_nop 0
	global_load_lds_dwordx4 v[212:213], off
	s_cmp_eq_u32 s100, 1
	s_cbranch_scc1 .Lmy_sk4_pk
	s_waitcnt vmcnt(8)
.Lmy_sk4_pk:
	s_waitcnt lgkmcnt(0)
	s_setprio 1
	s_barrier
	v_mfma_f32_16x16x32_bf16 v[62:65], v[90:93], v[164:167], 0
	v_mfma_f32_16x16x32_bf16 v[58:61], v[100:103], v[164:167], 0
	v_mfma_f32_16x16x32_bf16 v[46:49], v[90:93], v[172:175], 0
	v_mfma_f32_16x16x32_bf16 v[42:45], v[100:103], v[172:175], 0
	v_mfma_f32_16x16x32_bf16 v[30:33], v[90:93], v[180:183], 0
	v_mfma_f32_16x16x32_bf16 v[26:29], v[100:103], v[180:183], 0
	v_mfma_f32_16x16x32_bf16 v[14:17], v[90:93], v[188:191], 0
	v_mfma_f32_16x16x32_bf16 v[10:13], v[100:103], v[188:191], 0
	v_mfma_f32_16x16x32_bf16 v[62:65], v[94:97], v[168:171], v[62:65]
	v_mfma_f32_16x16x32_bf16 v[58:61], v[104:107], v[168:171], v[58:61]
	v_mfma_f32_16x16x32_bf16 v[46:49], v[94:97], v[176:179], v[46:49]
	v_mfma_f32_16x16x32_bf16 v[42:45], v[104:107], v[176:179], v[42:45]
	v_mfma_f32_16x16x32_bf16 v[30:33], v[94:97], v[184:187], v[30:33]
	v_mfma_f32_16x16x32_bf16 v[26:29], v[104:107], v[184:187], v[26:29]
	v_mfma_f32_16x16x32_bf16 v[14:17], v[94:97], v[192:195], v[14:17]
	v_mfma_f32_16x16x32_bf16 v[10:13], v[104:107], v[192:195], v[10:13]
	s_setprio 0
	s_setprio 1
	v_mfma_f32_16x16x32_bf16 v[54:57], v[108:111], v[164:167], 0
	v_mfma_f32_16x16x32_bf16 v[50:53], v[120:123], v[164:167], 0
	v_mfma_f32_16x16x32_bf16 v[38:41], v[108:111], v[172:175], 0
	v_mfma_f32_16x16x32_bf16 v[34:37], v[120:123], v[172:175], 0
	v_mfma_f32_16x16x32_bf16 v[22:25], v[108:111], v[180:183], 0
	v_mfma_f32_16x16x32_bf16 v[18:21], v[120:123], v[180:183], 0
	v_mfma_f32_16x16x32_bf16 v[6:9], v[108:111], v[188:191], 0
	v_mfma_f32_16x16x32_bf16 v[2:5], v[120:123], v[188:191], 0
	v_mfma_f32_16x16x32_bf16 v[54:57], v[112:115], v[168:171], v[54:57]
	v_mfma_f32_16x16x32_bf16 v[50:53], v[128:131], v[168:171], v[50:53]
	v_mfma_f32_16x16x32_bf16 v[38:41], v[112:115], v[176:179], v[38:41]
	v_mfma_f32_16x16x32_bf16 v[34:37], v[128:131], v[176:179], v[34:37]
	v_mfma_f32_16x16x32_bf16 v[22:25], v[112:115], v[184:187], v[22:25]
	v_mfma_f32_16x16x32_bf16 v[18:21], v[128:131], v[184:187], v[18:21]
	v_mfma_f32_16x16x32_bf16 v[6:9], v[112:115], v[192:195], v[6:9]
	v_mfma_f32_16x16x32_bf16 v[2:5], v[128:131], v[192:195], v[2:5]
	s_setprio 0
	s_barrier
	s_add_i32 s6, 0, 0x18000
	s_add_i32 s7, 0, 0x1c000
	v_add_u32_e32 v104, s6, v239
	v_add_u32_e32 v128, s7, v239
	ds_read_b128 v[90:93], v104
	ds_read_b128 v[94:97], v104 offset:1024
	ds_read_b128 v[100:103], v104 offset:2048
	ds_read_b128 v[104:107], v104 offset:3072
	ds_read_b128 v[108:111], v128
	ds_read_b128 v[112:115], v128 offset:1024
	ds_read_b128 v[120:123], v128 offset:2048
	ds_read_b128 v[128:131], v128 offset:3072
	s_add_u32 s4, s74, 0x40000
	s_addc_u32 s5, s75, 0
	v_lshl_add_u64 v[214:215], s[4:5], 0, v[98:99]
	s_add_i32 m0, s44, 0x4000
	ds_read_b128 v[164:167], v241 offset:32768
	ds_read_b128 v[168:171], v241 offset:33792
	ds_read_b128 v[172:175], v241 offset:34816
	ds_read_b128 v[176:179], v241 offset:35840
	ds_read_b128 v[180:183], v241 offset:36864
	ds_read_b128 v[184:187], v241 offset:37888
	ds_read_b128 v[188:191], v241 offset:38912
	ds_read_b128 v[192:195], v241 offset:39936
	global_load_lds_dwordx4 v[214:215], off
	v_lshl_add_u64 v[214:215], s[4:5], 0, v[206:207]
	s_add_i32 m0, s44, 0x6000
	s_nop 0
	global_load_lds_dwordx4 v[214:215], off
	s_waitcnt vmcnt(8)
	s_waitcnt lgkmcnt(0)
	s_setprio 1
	s_barrier
	v_mfma_f32_16x16x32_bf16 v[160:163], v[90:93], v[164:167], v[160:163]
	v_mfma_f32_16x16x32_bf16 v[156:159], v[100:103], v[164:167], v[156:159]
	v_mfma_f32_16x16x32_bf16 v[144:147], v[90:93], v[172:175], v[144:147]
	v_mfma_f32_16x16x32_bf16 v[140:143], v[100:103], v[172:175], v[140:143]
	v_mfma_f32_16x16x32_bf16 v[124:127], v[90:93], v[180:183], v[124:127]
	v_mfma_f32_16x16x32_bf16 v[116:119], v[100:103], v[180:183], v[116:119]
	v_mfma_f32_16x16x32_bf16 v[78:81], v[90:93], v[188:191], v[78:81]
	v_mfma_f32_16x16x32_bf16 v[74:77], v[100:103], v[188:191], v[74:77]
	v_mfma_f32_16x16x32_bf16 v[160:163], v[94:97], v[168:171], v[160:163]
	v_mfma_f32_16x16x32_bf16 v[156:159], v[104:107], v[168:171], v[156:159]
	v_mfma_f32_16x16x32_bf16 v[144:147], v[94:97], v[176:179], v[144:147]
	v_mfma_f32_16x16x32_bf16 v[140:143], v[104:107], v[176:179], v[140:143]
	v_mfma_f32_16x16x32_bf16 v[124:127], v[94:97], v[184:187], v[124:127]
	v_mfma_f32_16x16x32_bf16 v[116:119], v[104:107], v[184:187], v[116:119]
	v_mfma_f32_16x16x32_bf16 v[78:81], v[94:97], v[192:195], v[78:81]
	v_mfma_f32_16x16x32_bf16 v[74:77], v[104:107], v[192:195], v[74:77]
	s_setprio 0
	s_setprio 1
	v_mfma_f32_16x16x32_bf16 v[152:155], v[108:111], v[164:167], v[152:155]
	v_mfma_f32_16x16x32_bf16 v[148:151], v[120:123], v[164:167], v[148:151]
	v_mfma_f32_16x16x32_bf16 v[136:139], v[108:111], v[172:175], v[136:139]
	v_mfma_f32_16x16x32_bf16 v[132:135], v[120:123], v[172:175], v[132:135]
	v_mfma_f32_16x16x32_bf16 v[86:89], v[108:111], v[180:183], v[86:89]
	v_mfma_f32_16x16x32_bf16 v[82:85], v[120:123], v[180:183], v[82:85]
	v_mfma_f32_16x16x32_bf16 v[70:73], v[108:111], v[188:191], v[70:73]
	v_mfma_f32_16x16x32_bf16 v[66:69], v[120:123], v[188:191], v[66:69]
	v_mfma_f32_16x16x32_bf16 v[152:155], v[112:115], v[168:171], v[152:155]
	v_mfma_f32_16x16x32_bf16 v[148:151], v[128:131], v[168:171], v[148:151]
	v_mfma_f32_16x16x32_bf16 v[136:139], v[112:115], v[176:179], v[136:139]
	v_mfma_f32_16x16x32_bf16 v[132:135], v[128:131], v[176:179], v[132:135]
	v_mfma_f32_16x16x32_bf16 v[86:89], v[112:115], v[184:187], v[86:89]
	v_mfma_f32_16x16x32_bf16 v[82:85], v[128:131], v[184:187], v[82:85]
	v_mfma_f32_16x16x32_bf16 v[70:73], v[112:115], v[192:195], v[70:73]
	v_mfma_f32_16x16x32_bf16 v[66:69], v[128:131], v[192:195], v[66:69]
	s_setprio 0
	s_barrier
	s_add_i32 s4, s6, s91
	v_lshl_add_u64 v[200:201], v[200:201], 0, s[42:43]
	s_mov_b32 m0, s4
	ds_read_b128 v[164:167], v241 offset:49152
	ds_read_b128 v[168:171], v241 offset:50176
	ds_read_b128 v[172:175], v241 offset:51200
	ds_read_b128 v[176:179], v241 offset:52224
	ds_read_b128 v[180:183], v241 offset:53248
	ds_read_b128 v[184:187], v241 offset:54272
	ds_read_b128 v[188:191], v241 offset:55296
	ds_read_b128 v[192:195], v241 offset:56320
	global_load_lds_dwordx4 v[200:201], off
	s_add_i32 m0, s4, 0x2000
	s_add_u32 s4, s70, 0x40080
	v_lshl_add_u64 v[200:201], v[202:203], 0, s[42:43]
	s_addc_u32 s5, s71, 0
	s_add_i32 s6, s7, s91
	global_load_lds_dwordx4 v[200:201], off
	v_lshl_add_u64 v[200:201], s[4:5], 0, v[204:205]
	s_mov_b32 m0, s6
	s_nop 0
	global_load_lds_dwordx4 v[200:201], off
	v_lshl_add_u64 v[200:201], s[4:5], 0, v[208:209]
	s_add_i32 m0, s6, 0x2000
	s_nop 0
	global_load_lds_dwordx4 v[200:201], off
	v_lshl_add_u64 v[200:201], v[210:211], 0, s[42:43]
	s_add_i32 m0, s44, 0x8000
	s_nop 0
	global_load_lds_dwordx4 v[200:201], off
	v_lshl_add_u64 v[200:201], v[212:213], 0, s[42:43]
	s_add_i32 m0, s44, 0xa000
	s_nop 0
	global_load_lds_dwordx4 v[200:201], off
	s_waitcnt vmcnt(8)
	s_waitcnt lgkmcnt(0)
	s_setprio 1
	s_barrier
	v_mfma_f32_16x16x32_bf16 v[62:65], v[90:93], v[164:167], v[62:65]
	v_mfma_f32_16x16x32_bf16 v[58:61], v[100:103], v[164:167], v[58:61]
	v_mfma_f32_16x16x32_bf16 v[46:49], v[90:93], v[172:175], v[46:49]
	v_mfma_f32_16x16x32_bf16 v[42:45], v[100:103], v[172:175], v[42:45]
	v_mfma_f32_16x16x32_bf16 v[30:33], v[90:93], v[180:183], v[30:33]
	v_mfma_f32_16x16x32_bf16 v[26:29], v[100:103], v[180:183], v[26:29]
	v_mfma_f32_16x16x32_bf16 v[14:17], v[90:93], v[188:191], v[14:17]
	v_mfma_f32_16x16x32_bf16 v[10:13], v[100:103], v[188:191], v[10:13]
	v_mfma_f32_16x16x32_bf16 v[62:65], v[94:97], v[168:171], v[62:65]
	v_mfma_f32_16x16x32_bf16 v[58:61], v[104:107], v[168:171], v[58:61]
	v_mfma_f32_16x16x32_bf16 v[46:49], v[94:97], v[176:179], v[46:49]
	v_mfma_f32_16x16x32_bf16 v[42:45], v[104:107], v[176:179], v[42:45]
	v_mfma_f32_16x16x32_bf16 v[30:33], v[94:97], v[184:187], v[30:33]
	v_mfma_f32_16x16x32_bf16 v[26:29], v[104:107], v[184:187], v[26:29]
	v_mfma_f32_16x16x32_bf16 v[14:17], v[94:97], v[192:195], v[14:17]
	v_mfma_f32_16x16x32_bf16 v[10:13], v[104:107], v[192:195], v[10:13]
	s_setprio 0
	s_setprio 1
	v_mfma_f32_16x16x32_bf16 v[54:57], v[108:111], v[164:167], v[54:57]
	v_mfma_f32_16x16x32_bf16 v[50:53], v[120:123], v[164:167], v[50:53]
	v_mfma_f32_16x16x32_bf16 v[38:41], v[108:111], v[172:175], v[38:41]
	v_mfma_f32_16x16x32_bf16 v[34:37], v[120:123], v[172:175], v[34:37]
	v_mfma_f32_16x16x32_bf16 v[22:25], v[108:111], v[180:183], v[22:25]
	v_mfma_f32_16x16x32_bf16 v[18:21], v[120:123], v[180:183], v[18:21]
	v_mfma_f32_16x16x32_bf16 v[6:9], v[108:111], v[188:191], v[6:9]
	v_mfma_f32_16x16x32_bf16 v[2:5], v[120:123], v[188:191], v[2:5]
	v_mfma_f32_16x16x32_bf16 v[54:57], v[112:115], v[168:171], v[54:57]
	v_mfma_f32_16x16x32_bf16 v[50:53], v[128:131], v[168:171], v[50:53]
	v_mfma_f32_16x16x32_bf16 v[38:41], v[112:115], v[176:179], v[38:41]
	v_mfma_f32_16x16x32_bf16 v[34:37], v[128:131], v[176:179], v[34:37]
	v_mfma_f32_16x16x32_bf16 v[22:25], v[112:115], v[184:187], v[22:25]
	v_mfma_f32_16x16x32_bf16 v[18:21], v[128:131], v[184:187], v[18:21]
	v_mfma_f32_16x16x32_bf16 v[6:9], v[112:115], v[192:195], v[6:9]
	v_mfma_f32_16x16x32_bf16 v[2:5], v[128:131], v[192:195], v[2:5]
	s_setprio 0
	s_barrier
	s_mov_b32 s100, 0
	s_add_i32 s97, s97, 2
	s_add_u32 s68, s68, 0x100
	s_addc_u32 s69, s69, 0
	s_add_u32 vcc_hi, vcc_hi, 0x100
	s_addc_u32 s96, s96, 0
	s_cmp_gt_u32 s97, 13

.LBB0_907:
	s_ashr_i32 s21, s20, 31
	s_lshl_b64 s[30:31], s[20:21], 19
	v_readlane_b32 s2, v254, 23
	s_add_u32 s30, s2, s30
	v_readlane_b32 s2, v254, 24
	s_addc_u32 s31, s2, s31
	s_and_b64 s[40:41], s[38:39], exec
	s_cselect_b32 s21, s31, s57
	s_cselect_b32 s93, s30, s56
	s_ashr_i32 s53, s52, 31
	s_lshl_b64 s[40:41], s[52:53], 19
	s_add_u32 s40, s27, s40
	s_addc_u32 s41, s77, s41
	s_and_b64 s[44:45], s[38:39], exec
	s_cselect_b32 s15, s41, s69
	s_cselect_b32 s94, s40, s68
	s_add_u32 s56, s56, 0x40080
	s_addc_u32 s57, s57, 0
	s_add_u32 s95, s68, 0x100
	s_addc_u32 vcc_lo, s69, 0
	s_mov_b32 s96, -2
	s_add_u32 s4, s56, 0xfffc0080
	s_addc_u32 s5, s57, -1
	s_add_i32 s45, 0, 0x10000
	s_cmp_eq_u32 s96, 12
	s_cselect_b32 s71, s21, s5
	s_cselect_b32 s70, s93, s4
	s_cselect_b32 s69, s15, vcc_lo
	s_cselect_b32 s68, s94, s95
	s_add_i32 s97, 0, 0x14000
	v_add_u32_e32 v104, s45, v223
	v_add_u32_e32 v124, s97, v223
	ds_read_b128 v[86:89], v104
	ds_read_b128 v[90:93], v104 offset:1024
	ds_read_b128 v[100:103], v104 offset:2048
	ds_read_b128 v[104:107], v104 offset:3072
	ds_read_b128 v[108:111], v124
	ds_read_b128 v[112:115], v124 offset:1024
	ds_read_b128 v[116:119], v124 offset:2048
	ds_read_b128 v[124:127], v124 offset:3072
	s_add_i32 s44, s74, 0
	v_lshl_add_u64 v[200:201], s[56:57], 0, v[98:99]
	s_add_i32 m0, s44, 0xc000
	ds_read_b128 v[164:167], v225
	ds_read_b128 v[168:171], v225 offset:1024
	ds_read_b128 v[172:175], v225 offset:2048
	ds_read_b128 v[176:179], v225 offset:3072
	ds_read_b128 v[180:183], v225 offset:4096
	ds_read_b128 v[184:187], v225 offset:5120
	ds_read_b128 v[188:191], v225 offset:6144
	ds_read_b128 v[192:195], v225 offset:7168
	global_load_lds_dwordx4 v[200:201], off
	v_lshl_add_u64 v[200:201], s[56:57], 0, v[206:207]
	s_add_i32 m0, s44, 0xe000
	s_nop 0
	global_load_lds_dwordx4 v[200:201], off
	s_cmp_eq_u32 s100, 1
	s_cbranch_scc1 .Lmy_sk5_pk
	s_waitcnt vmcnt(8)
.Lmy_sk5_pk:
	s_waitcnt lgkmcnt(0)
	s_setprio 1
	s_barrier
	v_mfma_f32_16x16x32_bf16 v[160:163], v[86:89], v[164:167], 0
	v_mfma_f32_16x16x32_bf16 v[156:159], v[100:103], v[164:167], 0
	v_mfma_f32_16x16x32_bf16 v[144:147], v[86:89], v[172:175], 0
	v_mfma_f32_16x16x32_bf16 v[140:143], v[100:103], v[172:175], 0
	v_mfma_f32_16x16x32_bf16 v[128:131], v[86:89], v[180:183], 0
	v_mfma_f32_16x16x32_bf16 v[120:123], v[100:103], v[180:183], 0
	v_mfma_f32_16x16x32_bf16 v[78:81], v[86:89], v[188:191], 0
	v_mfma_f32_16x16x32_bf16 v[74:77], v[100:103], v[188:191], 0
	v_mfma_f32_16x16x32_bf16 v[160:163], v[90:93], v[168:171], v[160:163]
	v_mfma_f32_16x16x32_bf16 v[156:159], v[104:107], v[168:171], v[156:159]
	v_mfma_f32_16x16x32_bf16 v[144:147], v[90:93], v[176:179], v[144:147]
	v_mfma_f32_16x16x32_bf16 v[140:143], v[104:107], v[176:179], v[140:143]
	v_mfma_f32_16x16x32_bf16 v[128:131], v[90:93], v[184:187], v[128:131]
	v_mfma_f32_16x16x32_bf16 v[120:123], v[104:107], v[184:187], v[120:123]
	v_mfma_f32_16x16x32_bf16 v[78:81], v[90:93], v[192:195], v[78:81]
	v_mfma_f32_16x16x32_bf16 v[74:77], v[104:107], v[192:195], v[74:77]
	s_setprio 0
	s_setprio 1
	v_mfma_f32_16x16x32_bf16 v[152:155], v[108:111], v[164:167], 0
	v_mfma_f32_16x16x32_bf16 v[148:151], v[116:119], v[164:167], 0
	v_mfma_f32_16x16x32_bf16 v[136:139], v[108:111], v[172:175], 0
	v_mfma_f32_16x16x32_bf16 v[132:135], v[116:119], v[172:175], 0
	v_mfma_f32_16x16x32_bf16 v[94:97], v[108:111], v[180:183], 0
	v_mfma_f32_16x16x32_bf16 v[82:85], v[116:119], v[180:183], 0
	v_mfma_f32_16x16x32_bf16 v[70:73], v[108:111], v[188:191], 0
	v_mfma_f32_16x16x32_bf16 v[66:69], v[116:119], v[188:191], 0
	v_mfma_f32_16x16x32_bf16 v[152:155], v[112:115], v[168:171], v[152:155]
	v_mfma_f32_16x16x32_bf16 v[148:151], v[124:127], v[168:171], v[148:151]
	v_mfma_f32_16x16x32_bf16 v[136:139], v[112:115], v[176:179], v[136:139]
	v_mfma_f32_16x16x32_bf16 v[132:135], v[124:127], v[176:179], v[132:135]
	v_mfma_f32_16x16x32_bf16 v[94:97], v[112:115], v[184:187], v[94:97]
	v_mfma_f32_16x16x32_bf16 v[82:85], v[124:127], v[184:187], v[82:85]
	v_mfma_f32_16x16x32_bf16 v[70:73], v[112:115], v[192:195], v[70:73]
	v_mfma_f32_16x16x32_bf16 v[66:69], v[124:127], v[192:195], v[66:69]
	s_setprio 0
	s_barrier
	s_add_i32 s4, s45, s74
	v_lshl_add_u64 v[200:201], s[68:69], 0, v[204:205]
	s_mov_b32 m0, s4
	ds_read_b128 v[164:167], v225 offset:16384
	ds_read_b128 v[168:171], v225 offset:17408
	ds_read_b128 v[172:175], v225 offset:18432
	ds_read_b128 v[176:179], v225 offset:19456
	ds_read_b128 v[180:183], v225 offset:20480
	ds_read_b128 v[184:187], v225 offset:21504
	ds_read_b128 v[188:191], v225 offset:22528
	ds_read_b128 v[192:195], v225 offset:23552
	global_load_lds_dwordx4 v[200:201], off
	s_add_i32 m0, s4, 0x2000
	s_add_u32 s4, s68, 0x40000
	v_lshl_add_u64 v[202:203], s[68:69], 0, v[208:209]
	s_addc_u32 s5, s69, 0
	s_add_i32 s45, s97, s74
	global_load_lds_dwordx4 v[202:203], off
	v_lshl_add_u64 v[210:211], s[4:5], 0, v[204:205]
	s_mov_b32 m0, s45
	v_lshl_add_u64 v[212:213], s[70:71], 0, v[206:207]
	global_load_lds_dwordx4 v[210:211], off
	v_lshl_add_u64 v[210:211], s[4:5], 0, v[208:209]
	s_add_i32 m0, s45, 0x2000
	s_nop 0
	global_load_lds_dwordx4 v[210:211], off
	v_lshl_add_u64 v[210:211], s[70:71], 0, v[98:99]
	s_mov_b32 m0, s44
	s_nop 0
	global_load_lds_dwordx4 v[210:211], off
	s_add_i32 m0, s44, 0x2000
	s_nop 0
	global_load_lds_dwordx4 v[212:213], off
	s_cmp_eq_u32 s100, 1
	s_cbranch_scc1 .Lmy_sk6_pk
	s_waitcnt vmcnt(8)
.Lmy_sk6_pk:
	s_waitcnt lgkmcnt(0)
	s_setprio 1
	s_barrier
	v_mfma_f32_16x16x32_bf16 v[62:65], v[86:89], v[164:167], 0
	v_mfma_f32_16x16x32_bf16 v[58:61], v[100:103], v[164:167], 0
	v_mfma_f32_16x16x32_bf16 v[46:49], v[86:89], v[172:175], 0
	v_mfma_f32_16x16x32_bf16 v[42:45], v[100:103], v[172:175], 0
	v_mfma_f32_16x16x32_bf16 v[30:33], v[86:89], v[180:183], 0
	v_mfma_f32_16x16x32_bf16 v[26:29], v[100:103], v[180:183], 0
	v_mfma_f32_16x16x32_bf16 v[14:17], v[86:89], v[188:191], 0
	v_mfma_f32_16x16x32_bf16 v[10:13], v[100:103], v[188:191], 0
	v_mfma_f32_16x16x32_bf16 v[62:65], v[90:93], v[168:171], v[62:65]
	v_mfma_f32_16x16x32_bf16 v[58:61], v[104:107], v[168:171], v[58:61]
	v_mfma_f32_16x16x32_bf16 v[46:49], v[90:93], v[176:179], v[46:49]
	v_mfma_f32_16x16x32_bf16 v[42:45], v[104:107], v[176:179], v[42:45]
	v_mfma_f32_16x16x32_bf16 v[30:33], v[90:93], v[184:187], v[30:33]
	v_mfma_f32_16x16x32_bf16 v[26:29], v[104:107], v[184:187], v[26:29]
	v_mfma_f32_16x16x32_bf16 v[14:17], v[90:93], v[192:195], v[14:17]
	v_mfma_f32_16x16x32_bf16 v[10:13], v[104:107], v[192:195], v[10:13]
	s_setprio 0
	s_setprio 1
	v_mfma_f32_16x16x32_bf16 v[54:57], v[108:111], v[164:167], 0
	v_mfma_f32_16x16x32_bf16 v[50:53], v[116:119], v[164:167], 0
	v_mfma_f32_16x16x32_bf16 v[38:41], v[108:111], v[172:175], 0
	v_mfma_f32_16x16x32_bf16 v[34:37], v[116:119], v[172:175], 0
	v_mfma_f32_16x16x32_bf16 v[22:25], v[108:111], v[180:183], 0
	v_mfma_f32_16x16x32_bf16 v[18:21], v[116:119], v[180:183], 0
	v_mfma_f32_16x16x32_bf16 v[6:9], v[108:111], v[188:191], 0
	v_mfma_f32_16x16x32_bf16 v[2:5], v[116:119], v[188:191], 0
	v_mfma_f32_16x16x32_bf16 v[54:57], v[112:115], v[168:171], v[54:57]
	v_mfma_f32_16x16x32_bf16 v[50:53], v[124:127], v[168:171], v[50:53]
	v_mfma_f32_16x16x32_bf16 v[38:41], v[112:115], v[176:179], v[38:41]
	v_mfma_f32_16x16x32_bf16 v[34:37], v[124:127], v[176:179], v[34:37]
	v_mfma_f32_16x16x32_bf16 v[22:25], v[112:115], v[184:187], v[22:25]
	v_mfma_f32_16x16x32_bf16 v[18:21], v[124:127], v[184:187], v[18:21]
	v_mfma_f32_16x16x32_bf16 v[6:9], v[112:115], v[192:195], v[6:9]
	v_mfma_f32_16x16x32_bf16 v[2:5], v[124:127], v[192:195], v[2:5]
	s_setprio 0
	s_barrier
	s_add_i32 s45, 0, 0x18000
	s_add_i32 s97, 0, 0x1c000
	v_add_u32_e32 v104, s45, v223
	v_add_u32_e32 v124, s97, v223
	ds_read_b128 v[86:89], v104
	ds_read_b128 v[90:93], v104 offset:1024
	ds_read_b128 v[100:103], v104 offset:2048
	ds_read_b128 v[104:107], v104 offset:3072
	ds_read_b128 v[108:111], v124
	ds_read_b128 v[112:115], v124 offset:1024
	ds_read_b128 v[116:119], v124 offset:2048
	ds_read_b128 v[124:127], v124 offset:3072
	s_add_u32 s4, s70, 0x40000
	s_addc_u32 s5, s71, 0
	v_lshl_add_u64 v[214:215], s[4:5], 0, v[98:99]
	s_add_i32 m0, s44, 0x4000
	ds_read_b128 v[164:167], v225 offset:32768
	ds_read_b128 v[168:171], v225 offset:33792
	ds_read_b128 v[172:175], v225 offset:34816
	ds_read_b128 v[176:179], v225 offset:35840
	ds_read_b128 v[180:183], v225 offset:36864
	ds_read_b128 v[184:187], v225 offset:37888
	ds_read_b128 v[188:191], v225 offset:38912
	ds_read_b128 v[192:195], v225 offset:39936
	global_load_lds_dwordx4 v[214:215], off
	v_lshl_add_u64 v[214:215], s[4:5], 0, v[206:207]
	s_add_i32 m0, s44, 0x6000
	s_nop 0
	global_load_lds_dwordx4 v[214:215], off
	s_waitcnt vmcnt(8)
	s_waitcnt lgkmcnt(0)
	s_setprio 1
	s_barrier
	v_mfma_f32_16x16x32_bf16 v[160:163], v[86:89], v[164:167], v[160:163]
	v_mfma_f32_16x16x32_bf16 v[156:159], v[100:103], v[164:167], v[156:159]
	v_mfma_f32_16x16x32_bf16 v[144:147], v[86:89], v[172:175], v[144:147]
	v_mfma_f32_16x16x32_bf16 v[140:143], v[100:103], v[172:175], v[140:143]
	v_mfma_f32_16x16x32_bf16 v[128:131], v[86:89], v[180:183], v[128:131]
	v_mfma_f32_16x16x32_bf16 v[120:123], v[100:103], v[180:183], v[120:123]
	v_mfma_f32_16x16x32_bf16 v[78:81], v[86:89], v[188:191], v[78:81]
	v_mfma_f32_16x16x32_bf16 v[74:77], v[100:103], v[188:191], v[74:77]
	v_mfma_f32_16x16x32_bf16 v[160:163], v[90:93], v[168:171], v[160:163]
	v_mfma_f32_16x16x32_bf16 v[156:159], v[104:107], v[168:171], v[156:159]
	v_mfma_f32_16x16x32_bf16 v[144:147], v[90:93], v[176:179], v[144:147]
	v_mfma_f32_16x16x32_bf16 v[140:143], v[104:107], v[176:179], v[140:143]
	v_mfma_f32_16x16x32_bf16 v[128:131], v[90:93], v[184:187], v[128:131]
	v_mfma_f32_16x16x32_bf16 v[120:123], v[104:107], v[184:187], v[120:123]
	v_mfma_f32_16x16x32_bf16 v[78:81], v[90:93], v[192:195], v[78:81]
	v_mfma_f32_16x16x32_bf16 v[74:77], v[104:107], v[192:195], v[74:77]
	s_setprio 0
	s_setprio 1
	v_mfma_f32_16x16x32_bf16 v[152:155], v[108:111], v[164:167], v[152:155]
	v_mfma_f32_16x16x32_bf16 v[148:151], v[116:119], v[164:167], v[148:151]
	v_mfma_f32_16x16x32_bf16 v[136:139], v[108:111], v[172:175], v[136:139]
	v_mfma_f32_16x16x32_bf16 v[132:135], v[116:119], v[172:175], v[132:135]
	v_mfma_f32_16x16x32_bf16 v[94:97], v[108:111], v[180:183], v[94:97]
	v_mfma_f32_16x16x32_bf16 v[82:85], v[116:119], v[180:183], v[82:85]
	v_mfma_f32_16x16x32_bf16 v[70:73], v[108:111], v[188:191], v[70:73]
	v_mfma_f32_16x16x32_bf16 v[66:69], v[116:119], v[188:191], v[66:69]
	v_mfma_f32_16x16x32_bf16 v[152:155], v[112:115], v[168:171], v[152:155]
	v_mfma_f32_16x16x32_bf16 v[148:151], v[124:127], v[168:171], v[148:151]
	v_mfma_f32_16x16x32_bf16 v[136:139], v[112:115], v[176:179], v[136:139]
	v_mfma_f32_16x16x32_bf16 v[132:135], v[124:127], v[176:179], v[132:135]
	v_mfma_f32_16x16x32_bf16 v[94:97], v[112:115], v[184:187], v[94:97]
	v_mfma_f32_16x16x32_bf16 v[82:85], v[124:127], v[184:187], v[82:85]
	v_mfma_f32_16x16x32_bf16 v[70:73], v[112:115], v[192:195], v[70:73]
	v_mfma_f32_16x16x32_bf16 v[66:69], v[124:127], v[192:195], v[66:69]
	s_setprio 0
	s_barrier
	s_add_i32 s4, s45, s74
	v_lshl_add_u64 v[200:201], v[200:201], 0, s[42:43]
	s_mov_b32 m0, s4
	ds_read_b128 v[164:167], v225 offset:49152
	ds_read_b128 v[168:171], v225 offset:50176
	ds_read_b128 v[172:175], v225 offset:51200
	ds_read_b128 v[176:179], v225 offset:52224
	ds_read_b128 v[180:183], v225 offset:53248
	ds_read_b128 v[184:187], v225 offset:54272
	ds_read_b128 v[188:191], v225 offset:55296
	ds_read_b128 v[192:195], v225 offset:56320
	global_load_lds_dwordx4 v[200:201], off
	s_add_i32 m0, s4, 0x2000
	s_add_u32 s4, s68, 0x40080
	v_lshl_add_u64 v[200:201], v[202:203], 0, s[42:43]
	s_addc_u32 s5, s69, 0
	s_add_i32 s45, s97, s74
	global_load_lds_dwordx4 v[200:201], off
	v_lshl_add_u64 v[200:201], s[4:5], 0, v[204:205]
	s_mov_b32 m0, s45
	s_nop 0
	global_load_lds_dwordx4 v[200:201], off
	v_lshl_add_u64 v[200:201], s[4:5], 0, v[208:209]
	s_add_i32 m0, s45, 0x2000
	s_nop 0
	global_load_lds_dwordx4 v[200:201], off
	v_lshl_add_u64 v[200:201], v[210:211], 0, s[42:43]
	s_add_i32 m0, s44, 0x8000
	s_nop 0
	global_load_lds_dwordx4 v[200:201], off
	v_lshl_add_u64 v[200:201], v[212:213], 0, s[42:43]
	s_add_i32 m0, s44, 0xa000
	s_nop 0
	global_load_lds_dwordx4 v[200:201], off
	s_waitcnt vmcnt(8)
	s_waitcnt lgkmcnt(0)
	s_setprio 1
	s_barrier
	v_mfma_f32_16x16x32_bf16 v[62:65], v[86:89], v[164:167], v[62:65]
	v_mfma_f32_16x16x32_bf16 v[58:61], v[100:103], v[164:167], v[58:61]
	v_mfma_f32_16x16x32_bf16 v[46:49], v[86:89], v[172:175], v[46:49]
	v_mfma_f32_16x16x32_bf16 v[42:45], v[100:103], v[172:175], v[42:45]
	v_mfma_f32_16x16x32_bf16 v[30:33], v[86:89], v[180:183], v[30:33]
	v_mfma_f32_16x16x32_bf16 v[26:29], v[100:103], v[180:183], v[26:29]
	v_mfma_f32_16x16x32_bf16 v[14:17], v[86:89], v[188:191], v[14:17]
	v_mfma_f32_16x16x32_bf16 v[10:13], v[100:103], v[188:191], v[10:13]
	v_mfma_f32_16x16x32_bf16 v[62:65], v[90:93], v[168:171], v[62:65]
	v_mfma_f32_16x16x32_bf16 v[58:61], v[104:107], v[168:171], v[58:61]
	v_mfma_f32_16x16x32_bf16 v[46:49], v[90:93], v[176:179], v[46:49]
	v_mfma_f32_16x16x32_bf16 v[42:45], v[104:107], v[176:179], v[42:45]
	v_mfma_f32_16x16x32_bf16 v[30:33], v[90:93], v[184:187], v[30:33]
	v_mfma_f32_16x16x32_bf16 v[26:29], v[104:107], v[184:187], v[26:29]
	v_mfma_f32_16x16x32_bf16 v[14:17], v[90:93], v[192:195], v[14:17]
	v_mfma_f32_16x16x32_bf16 v[10:13], v[104:107], v[192:195], v[10:13]
	s_setprio 0
	s_setprio 1
	v_mfma_f32_16x16x32_bf16 v[54:57], v[108:111], v[164:167], v[54:57]
	v_mfma_f32_16x16x32_bf16 v[50:53], v[116:119], v[164:167], v[50:53]
	v_mfma_f32_16x16x32_bf16 v[38:41], v[108:111], v[172:175], v[38:41]
	v_mfma_f32_16x16x32_bf16 v[34:37], v[116:119], v[172:175], v[34:37]
	v_mfma_f32_16x16x32_bf16 v[22:25], v[108:111], v[180:183], v[22:25]
	v_mfma_f32_16x16x32_bf16 v[18:21], v[116:119], v[180:183], v[18:21]
	v_mfma_f32_16x16x32_bf16 v[6:9], v[108:111], v[188:191], v[6:9]
	v_mfma_f32_16x16x32_bf16 v[2:5], v[116:119], v[188:191], v[2:5]
	v_mfma_f32_16x16x32_bf16 v[54:57], v[112:115], v[168:171], v[54:57]
	v_mfma_f32_16x16x32_bf16 v[50:53], v[124:127], v[168:171], v[50:53]
	v_mfma_f32_16x16x32_bf16 v[38:41], v[112:115], v[176:179], v[38:41]
	v_mfma_f32_16x16x32_bf16 v[34:37], v[124:127], v[176:179], v[34:37]
	v_mfma_f32_16x16x32_bf16 v[22:25], v[112:115], v[184:187], v[22:25]
	v_mfma_f32_16x16x32_bf16 v[18:21], v[124:127], v[184:187], v[18:21]
	v_mfma_f32_16x16x32_bf16 v[6:9], v[112:115], v[192:195], v[6:9]
	v_mfma_f32_16x16x32_bf16 v[2:5], v[124:127], v[192:195], v[2:5]
	s_setprio 0
	s_barrier
	s_mov_b32 s100, 0
	s_add_i32 s96, s96, 2
	s_add_u32 s56, s56, 0x100
	s_addc_u32 s57, s57, 0
	s_add_u32 s95, s95, 0x100
	s_addc_u32 vcc_lo, vcc_lo, 0
	s_cmp_gt_u32 s96, 13

.LBB0_1010:
	s_ashr_i32 s21, s20, 31
	s_lshl_b64 s[4:5], s[20:21], 19
	s_add_u32 s30, s22, s4
	s_addc_u32 s31, s23, s5
	s_and_b64 s[4:5], s[36:37], exec
	s_cselect_b32 s21, s31, s41
	s_cselect_b32 s88, s30, s40
	s_ashr_i32 s15, s14, 31
	s_lshl_b64 s[4:5], s[14:15], 19
	s_add_u32 s38, s18, s4
	s_addc_u32 s39, s27, s5
	s_and_b64 s[4:5], s[36:37], exec
	s_cselect_b32 s15, s39, s57
	s_cselect_b32 s89, s38, s56
	s_add_u32 s40, s40, 0x40080
	s_addc_u32 s41, s41, 0
	s_add_u32 s90, s56, 0x100
	s_addc_u32 s91, s57, 0
	s_mov_b32 s92, -2
	s_add_u32 s4, s40, 0xfffc0080
	s_addc_u32 s5, s41, -1
	s_add_i32 s6, 0, 0x10000
	s_cmp_eq_u32 s92, 12
	s_cselect_b32 s69, s21, s5
	s_cselect_b32 s68, s88, s4
	s_cselect_b32 s57, s15, s91
	s_cselect_b32 s56, s89, s90
	s_add_i32 s7, 0, 0x14000
	v_add_u32_e32 v144, s6, v189
	v_add_u32_e32 v160, s7, v189
	ds_read_b128 v[132:135], v144
	ds_read_b128 v[136:139], v144 offset:1024
	ds_read_b128 v[140:143], v144 offset:2048
	ds_read_b128 v[144:147], v144 offset:3072
	ds_read_b128 v[156:159], v160
	ds_read_b128 v[162:165], v160 offset:1024
	ds_read_b128 v[192:195], v160 offset:2048
	ds_read_b128 v[200:203], v160 offset:3072
	s_add_i32 s44, s70, 0
	v_lshl_add_u64 v[166:167], s[40:41], 0, v[98:99]
	s_add_i32 m0, s44, 0xc000
	ds_read_b128 v[204:207], v191
	ds_read_b128 v[208:211], v191 offset:1024
	ds_read_b128 v[212:215], v191 offset:2048
	ds_read_b128 v[216:219], v191 offset:3072
	ds_read_b128 v[220:223], v191 offset:4096
	ds_read_b128 v[224:227], v191 offset:5120
	ds_read_b128 v[238:241], v191 offset:6144
	ds_read_b128 v[242:245], v191 offset:7168
	global_load_lds_dwordx4 v[166:167], off
	v_lshl_add_u64 v[166:167], s[40:41], 0, v[150:151]
	s_add_i32 m0, s44, 0xe000
	s_nop 0
	global_load_lds_dwordx4 v[166:167], off
	s_cmp_eq_u32 s100, 1
	s_cbranch_scc1 .Lmy_sk7_pk
	s_waitcnt vmcnt(8)
.Lmy_sk7_pk:
	s_waitcnt lgkmcnt(0)
	s_setprio 1
	s_barrier
	v_mfma_f32_16x16x32_bf16 v[128:131], v[132:135], v[204:207], 0
	v_mfma_f32_16x16x32_bf16 v[124:127], v[140:143], v[204:207], 0
	v_mfma_f32_16x16x32_bf16 v[112:115], v[132:135], v[212:215], 0
	v_mfma_f32_16x16x32_bf16 v[108:111], v[140:143], v[212:215], 0
	v_mfma_f32_16x16x32_bf16 v[94:97], v[132:135], v[220:223], 0
	v_mfma_f32_16x16x32_bf16 v[90:93], v[140:143], v[220:223], 0
	v_mfma_f32_16x16x32_bf16 v[78:81], v[132:135], v[238:241], 0
	v_mfma_f32_16x16x32_bf16 v[74:77], v[140:143], v[238:241], 0
	v_mfma_f32_16x16x32_bf16 v[128:131], v[136:139], v[208:211], v[128:131]
	v_mfma_f32_16x16x32_bf16 v[124:127], v[144:147], v[208:211], v[124:127]
	v_mfma_f32_16x16x32_bf16 v[112:115], v[136:139], v[216:219], v[112:115]
	v_mfma_f32_16x16x32_bf16 v[108:111], v[144:147], v[216:219], v[108:111]
	v_mfma_f32_16x16x32_bf16 v[94:97], v[136:139], v[224:227], v[94:97]
	v_mfma_f32_16x16x32_bf16 v[90:93], v[144:147], v[224:227], v[90:93]
	v_mfma_f32_16x16x32_bf16 v[78:81], v[136:139], v[242:245], v[78:81]
	v_mfma_f32_16x16x32_bf16 v[74:77], v[144:147], v[242:245], v[74:77]
	s_setprio 0
	s_setprio 1
	v_mfma_f32_16x16x32_bf16 v[120:123], v[156:159], v[204:207], 0
	v_mfma_f32_16x16x32_bf16 v[116:119], v[192:195], v[204:207], 0
	v_mfma_f32_16x16x32_bf16 v[104:107], v[156:159], v[212:215], 0
	v_mfma_f32_16x16x32_bf16 v[100:103], v[192:195], v[212:215], 0
	v_mfma_f32_16x16x32_bf16 v[86:89], v[156:159], v[220:223], 0
	v_mfma_f32_16x16x32_bf16 v[82:85], v[192:195], v[220:223], 0
	v_mfma_f32_16x16x32_bf16 v[70:73], v[156:159], v[238:241], 0
	v_mfma_f32_16x16x32_bf16 v[66:69], v[192:195], v[238:241], 0
	v_mfma_f32_16x16x32_bf16 v[120:123], v[162:165], v[208:211], v[120:123]
	v_mfma_f32_16x16x32_bf16 v[116:119], v[200:203], v[208:211], v[116:119]
	v_mfma_f32_16x16x32_bf16 v[104:107], v[162:165], v[216:219], v[104:107]
	v_mfma_f32_16x16x32_bf16 v[100:103], v[200:203], v[216:219], v[100:103]
	v_mfma_f32_16x16x32_bf16 v[86:89], v[162:165], v[224:227], v[86:89]
	v_mfma_f32_16x16x32_bf16 v[82:85], v[200:203], v[224:227], v[82:85]
	v_mfma_f32_16x16x32_bf16 v[70:73], v[162:165], v[242:245], v[70:73]
	v_mfma_f32_16x16x32_bf16 v[66:69], v[200:203], v[242:245], v[66:69]
	s_setprio 0
	s_barrier
	s_add_i32 s4, s6, s70
	v_lshl_add_u64 v[166:167], s[56:57], 0, v[148:149]
	s_mov_b32 m0, s4
	ds_read_b128 v[204:207], v191 offset:16384
	ds_read_b128 v[208:211], v191 offset:17408
	ds_read_b128 v[212:215], v191 offset:18432
	ds_read_b128 v[216:219], v191 offset:19456
	ds_read_b128 v[220:223], v191 offset:20480
	ds_read_b128 v[224:227], v191 offset:21504
	ds_read_b128 v[238:241], v191 offset:22528
	ds_read_b128 v[242:245], v191 offset:23552
	global_load_lds_dwordx4 v[166:167], off
	s_add_i32 m0, s4, 0x2000
	s_add_u32 s4, s56, 0x40000
	v_lshl_add_u64 v[170:171], s[56:57], 0, v[152:153]
	s_addc_u32 s5, s57, 0
	s_add_i32 s6, s7, s70
	global_load_lds_dwordx4 v[170:171], off
	v_lshl_add_u64 v[176:177], s[4:5], 0, v[148:149]
	s_mov_b32 m0, s6
	v_lshl_add_u64 v[180:181], s[68:69], 0, v[150:151]
	global_load_lds_dwordx4 v[176:177], off
	v_lshl_add_u64 v[176:177], s[4:5], 0, v[152:153]
	s_add_i32 m0, s6, 0x2000
	s_nop 0
	global_load_lds_dwordx4 v[176:177], off
	v_lshl_add_u64 v[176:177], s[68:69], 0, v[98:99]
	s_mov_b32 m0, s44
	s_nop 0
	global_load_lds_dwordx4 v[176:177], off
	s_add_i32 m0, s44, 0x2000
	s_nop 0
	global_load_lds_dwordx4 v[180:181], off
	s_cmp_eq_u32 s100, 1
	s_cbranch_scc1 .Lmy_sk8_pk
	s_waitcnt vmcnt(8)
.Lmy_sk8_pk:
	s_waitcnt lgkmcnt(0)
	s_setprio 1
	s_barrier
	v_mfma_f32_16x16x32_bf16 v[62:65], v[132:135], v[204:207], 0
	v_mfma_f32_16x16x32_bf16 v[58:61], v[140:143], v[204:207], 0
	v_mfma_f32_16x16x32_bf16 v[46:49], v[132:135], v[212:215], 0
	v_mfma_f32_16x16x32_bf16 v[42:45], v[140:143], v[212:215], 0
	v_mfma_f32_16x16x32_bf16 v[30:33], v[132:135], v[220:223], 0
	v_mfma_f32_16x16x32_bf16 v[26:29], v[140:143], v[220:223], 0
	v_mfma_f32_16x16x32_bf16 v[14:17], v[132:135], v[238:241], 0
	v_mfma_f32_16x16x32_bf16 v[10:13], v[140:143], v[238:241], 0
	v_mfma_f32_16x16x32_bf16 v[62:65], v[136:139], v[208:211], v[62:65]
	v_mfma_f32_16x16x32_bf16 v[58:61], v[144:147], v[208:211], v[58:61]
	v_mfma_f32_16x16x32_bf16 v[46:49], v[136:139], v[216:219], v[46:49]
	v_mfma_f32_16x16x32_bf16 v[42:45], v[144:147], v[216:219], v[42:45]
	v_mfma_f32_16x16x32_bf16 v[30:33], v[136:139], v[224:227], v[30:33]
	v_mfma_f32_16x16x32_bf16 v[26:29], v[144:147], v[224:227], v[26:29]
	v_mfma_f32_16x16x32_bf16 v[14:17], v[136:139], v[242:245], v[14:17]
	v_mfma_f32_16x16x32_bf16 v[10:13], v[144:147], v[242:245], v[10:13]
	s_setprio 0
	s_setprio 1
	v_mfma_f32_16x16x32_bf16 v[54:57], v[156:159], v[204:207], 0
	v_mfma_f32_16x16x32_bf16 v[50:53], v[192:195], v[204:207], 0
	v_mfma_f32_16x16x32_bf16 v[38:41], v[156:159], v[212:215], 0
	v_mfma_f32_16x16x32_bf16 v[34:37], v[192:195], v[212:215], 0
	v_mfma_f32_16x16x32_bf16 v[22:25], v[156:159], v[220:223], 0
	v_mfma_f32_16x16x32_bf16 v[18:21], v[192:195], v[220:223], 0
	v_mfma_f32_16x16x32_bf16 v[6:9], v[156:159], v[238:241], 0
	v_mfma_f32_16x16x32_bf16 v[2:5], v[192:195], v[238:241], 0
	v_mfma_f32_16x16x32_bf16 v[54:57], v[162:165], v[208:211], v[54:57]
	v_mfma_f32_16x16x32_bf16 v[50:53], v[200:203], v[208:211], v[50:53]
	v_mfma_f32_16x16x32_bf16 v[38:41], v[162:165], v[216:219], v[38:41]
	v_mfma_f32_16x16x32_bf16 v[34:37], v[200:203], v[216:219], v[34:37]
	v_mfma_f32_16x16x32_bf16 v[22:25], v[162:165], v[224:227], v[22:25]
	v_mfma_f32_16x16x32_bf16 v[18:21], v[200:203], v[224:227], v[18:21]
	v_mfma_f32_16x16x32_bf16 v[6:9], v[162:165], v[242:245], v[6:9]
	v_mfma_f32_16x16x32_bf16 v[2:5], v[200:203], v[242:245], v[2:5]
	s_setprio 0
	s_barrier
	s_add_i32 s6, 0, 0x18000
	s_add_i32 s7, 0, 0x1c000
	v_add_u32_e32 v144, s6, v189
	v_add_u32_e32 v160, s7, v189
	ds_read_b128 v[132:135], v144
	ds_read_b128 v[136:139], v144 offset:1024
	ds_read_b128 v[140:143], v144 offset:2048
	ds_read_b128 v[144:147], v144 offset:3072
	ds_read_b128 v[156:159], v160
	ds_read_b128 v[162:165], v160 offset:1024
	ds_read_b128 v[192:195], v160 offset:2048
	ds_read_b128 v[200:203], v160 offset:3072
	s_add_u32 s4, s68, 0x40000
	s_addc_u32 s5, s69, 0
	v_lshl_add_u64 v[246:247], s[4:5], 0, v[98:99]
	s_add_i32 m0, s44, 0x4000
	ds_read_b128 v[204:207], v191 offset:32768
	ds_read_b128 v[208:211], v191 offset:33792
	ds_read_b128 v[212:215], v191 offset:34816
	ds_read_b128 v[216:219], v191 offset:35840
	ds_read_b128 v[220:223], v191 offset:36864
	ds_read_b128 v[224:227], v191 offset:37888
	ds_read_b128 v[238:241], v191 offset:38912
	ds_read_b128 v[242:245], v191 offset:39936
	global_load_lds_dwordx4 v[246:247], off
	v_lshl_add_u64 v[246:247], s[4:5], 0, v[150:151]
	s_add_i32 m0, s44, 0x6000
	s_nop 0
	global_load_lds_dwordx4 v[246:247], off
	s_waitcnt vmcnt(8)
	s_waitcnt lgkmcnt(0)
	s_setprio 1
	s_barrier
	v_mfma_f32_16x16x32_bf16 v[128:131], v[132:135], v[204:207], v[128:131]
	v_mfma_f32_16x16x32_bf16 v[124:127], v[140:143], v[204:207], v[124:127]
	v_mfma_f32_16x16x32_bf16 v[112:115], v[132:135], v[212:215], v[112:115]
	v_mfma_f32_16x16x32_bf16 v[108:111], v[140:143], v[212:215], v[108:111]
	v_mfma_f32_16x16x32_bf16 v[94:97], v[132:135], v[220:223], v[94:97]
	v_mfma_f32_16x16x32_bf16 v[90:93], v[140:143], v[220:223], v[90:93]
	v_mfma_f32_16x16x32_bf16 v[78:81], v[132:135], v[238:241], v[78:81]
	v_mfma_f32_16x16x32_bf16 v[74:77], v[140:143], v[238:241], v[74:77]
	v_mfma_f32_16x16x32_bf16 v[128:131], v[136:139], v[208:211], v[128:131]
	v_mfma_f32_16x16x32_bf16 v[124:127], v[144:147], v[208:211], v[124:127]
	v_mfma_f32_16x16x32_bf16 v[112:115], v[136:139], v[216:219], v[112:115]
	v_mfma_f32_16x16x32_bf16 v[108:111], v[144:147], v[216:219], v[108:111]
	v_mfma_f32_16x16x32_bf16 v[94:97], v[136:139], v[224:227], v[94:97]
	v_mfma_f32_16x16x32_bf16 v[90:93], v[144:147], v[224:227], v[90:93]
	v_mfma_f32_16x16x32_bf16 v[78:81], v[136:139], v[242:245], v[78:81]
	v_mfma_f32_16x16x32_bf16 v[74:77], v[144:147], v[242:245], v[74:77]
	s_setprio 0
	s_setprio 1
	v_mfma_f32_16x16x32_bf16 v[120:123], v[156:159], v[204:207], v[120:123]
	v_mfma_f32_16x16x32_bf16 v[116:119], v[192:195], v[204:207], v[116:119]
	v_mfma_f32_16x16x32_bf16 v[104:107], v[156:159], v[212:215], v[104:107]
	v_mfma_f32_16x16x32_bf16 v[100:103], v[192:195], v[212:215], v[100:103]
	v_mfma_f32_16x16x32_bf16 v[86:89], v[156:159], v[220:223], v[86:89]
	v_mfma_f32_16x16x32_bf16 v[82:85], v[192:195], v[220:223], v[82:85]
	v_mfma_f32_16x16x32_bf16 v[70:73], v[156:159], v[238:241], v[70:73]
	v_mfma_f32_16x16x32_bf16 v[66:69], v[192:195], v[238:241], v[66:69]
	v_mfma_f32_16x16x32_bf16 v[120:123], v[162:165], v[208:211], v[120:123]
	v_mfma_f32_16x16x32_bf16 v[116:119], v[200:203], v[208:211], v[116:119]
	v_mfma_f32_16x16x32_bf16 v[104:107], v[162:165], v[216:219], v[104:107]
	v_mfma_f32_16x16x32_bf16 v[100:103], v[200:203], v[216:219], v[100:103]
	v_mfma_f32_16x16x32_bf16 v[86:89], v[162:165], v[224:227], v[86:89]
	v_mfma_f32_16x16x32_bf16 v[82:85], v[200:203], v[224:227], v[82:85]
	v_mfma_f32_16x16x32_bf16 v[70:73], v[162:165], v[242:245], v[70:73]
	v_mfma_f32_16x16x32_bf16 v[66:69], v[200:203], v[242:245], v[66:69]
	s_setprio 0
	s_barrier
	s_add_i32 s4, s6, s70
	v_lshl_add_u64 v[166:167], v[166:167], 0, s[42:43]
	s_mov_b32 m0, s4
	ds_read_b128 v[204:207], v191 offset:49152
	ds_read_b128 v[208:211], v191 offset:50176
	ds_read_b128 v[212:215], v191 offset:51200
	ds_read_b128 v[216:219], v191 offset:52224
	ds_read_b128 v[220:223], v191 offset:53248
	ds_read_b128 v[224:227], v191 offset:54272
	ds_read_b128 v[238:241], v191 offset:55296
	ds_read_b128 v[242:245], v191 offset:56320
	global_load_lds_dwordx4 v[166:167], off
	s_add_i32 m0, s4, 0x2000
	s_add_u32 s4, s56, 0x40080
	v_lshl_add_u64 v[166:167], v[170:171], 0, s[42:43]
	s_addc_u32 s5, s57, 0
	s_add_i32 s6, s7, s70
	global_load_lds_dwordx4 v[166:167], off
	v_lshl_add_u64 v[166:167], s[4:5], 0, v[148:149]
	s_mov_b32 m0, s6
	s_nop 0
	global_load_lds_dwordx4 v[166:167], off
	v_lshl_add_u64 v[166:167], s[4:5], 0, v[152:153]
	s_add_i32 m0, s6, 0x2000
	s_nop 0
	global_load_lds_dwordx4 v[166:167], off
	v_lshl_add_u64 v[166:167], v[176:177], 0, s[42:43]
	s_add_i32 m0, s44, 0x8000
	s_nop 0
	global_load_lds_dwordx4 v[166:167], off
	v_lshl_add_u64 v[166:167], v[180:181], 0, s[42:43]
	s_add_i32 m0, s44, 0xa000
	s_nop 0
	global_load_lds_dwordx4 v[166:167], off
	s_waitcnt vmcnt(8)
	s_waitcnt lgkmcnt(0)
	s_setprio 1
	s_barrier
	v_mfma_f32_16x16x32_bf16 v[62:65], v[132:135], v[204:207], v[62:65]
	v_mfma_f32_16x16x32_bf16 v[58:61], v[140:143], v[204:207], v[58:61]
	v_mfma_f32_16x16x32_bf16 v[46:49], v[132:135], v[212:215], v[46:49]
	v_mfma_f32_16x16x32_bf16 v[42:45], v[140:143], v[212:215], v[42:45]
	v_mfma_f32_16x16x32_bf16 v[30:33], v[132:135], v[220:223], v[30:33]
	v_mfma_f32_16x16x32_bf16 v[26:29], v[140:143], v[220:223], v[26:29]
	v_mfma_f32_16x16x32_bf16 v[14:17], v[132:135], v[238:241], v[14:17]
	v_mfma_f32_16x16x32_bf16 v[10:13], v[140:143], v[238:241], v[10:13]
	v_mfma_f32_16x16x32_bf16 v[62:65], v[136:139], v[208:211], v[62:65]
	v_mfma_f32_16x16x32_bf16 v[58:61], v[144:147], v[208:211], v[58:61]
	v_mfma_f32_16x16x32_bf16 v[46:49], v[136:139], v[216:219], v[46:49]
	v_mfma_f32_16x16x32_bf16 v[42:45], v[144:147], v[216:219], v[42:45]
	v_mfma_f32_16x16x32_bf16 v[30:33], v[136:139], v[224:227], v[30:33]
	v_mfma_f32_16x16x32_bf16 v[26:29], v[144:147], v[224:227], v[26:29]
	v_mfma_f32_16x16x32_bf16 v[14:17], v[136:139], v[242:245], v[14:17]
	v_mfma_f32_16x16x32_bf16 v[10:13], v[144:147], v[242:245], v[10:13]
	s_setprio 0
	s_setprio 1
	v_mfma_f32_16x16x32_bf16 v[54:57], v[156:159], v[204:207], v[54:57]
	v_mfma_f32_16x16x32_bf16 v[50:53], v[192:195], v[204:207], v[50:53]
	v_mfma_f32_16x16x32_bf16 v[38:41], v[156:159], v[212:215], v[38:41]
	v_mfma_f32_16x16x32_bf16 v[34:37], v[192:195], v[212:215], v[34:37]
	v_mfma_f32_16x16x32_bf16 v[22:25], v[156:159], v[220:223], v[22:25]
	v_mfma_f32_16x16x32_bf16 v[18:21], v[192:195], v[220:223], v[18:21]
	v_mfma_f32_16x16x32_bf16 v[6:9], v[156:159], v[238:241], v[6:9]
	v_mfma_f32_16x16x32_bf16 v[2:5], v[192:195], v[238:241], v[2:5]
	v_mfma_f32_16x16x32_bf16 v[54:57], v[162:165], v[208:211], v[54:57]
	v_mfma_f32_16x16x32_bf16 v[50:53], v[200:203], v[208:211], v[50:53]
	v_mfma_f32_16x16x32_bf16 v[38:41], v[162:165], v[216:219], v[38:41]
	v_mfma_f32_16x16x32_bf16 v[34:37], v[200:203], v[216:219], v[34:37]
	v_mfma_f32_16x16x32_bf16 v[22:25], v[162:165], v[224:227], v[22:25]
	v_mfma_f32_16x16x32_bf16 v[18:21], v[200:203], v[224:227], v[18:21]
	v_mfma_f32_16x16x32_bf16 v[6:9], v[162:165], v[242:245], v[6:9]
	v_mfma_f32_16x16x32_bf16 v[2:5], v[200:203], v[242:245], v[2:5]
	s_setprio 0
	s_barrier
	s_mov_b32 s100, 0
	s_add_i32 s92, s92, 2
	s_add_u32 s40, s40, 0x100
	s_addc_u32 s41, s41, 0
	s_add_u32 s90, s90, 0x100
	s_addc_u32 s91, s91, 0
	s_cmp_gt_u32 s92, 13

.LBB0_1115:
	s_ashr_i32 s27, s26, 31
	s_lshl_b64 s[4:5], s[26:27], 21
	s_add_u32 s40, s24, s4
	s_addc_u32 s41, s25, s5
	s_and_b64 s[4:5], s[30:31], exec
	s_cselect_b32 s18, s41, s75
	s_cselect_b32 s21, s40, s74
	s_ashr_i32 s69, s68, 31
	s_lshl_b64 s[4:5], s[68:69], 21
	s_add_u32 s56, s77, s4
	s_addc_u32 s57, s88, s5
	s_and_b64 s[4:5], s[30:31], exec
	s_cselect_b32 s27, s57, s79
	s_cselect_b32 s69, s56, s78
	s_add_u32 s74, s74, 0x100080
	s_addc_u32 s75, s75, 0
	s_add_u32 s71, s78, 0x100
	s_addc_u32 s94, s79, 0
	s_mov_b32 s95, -2
	s_waitcnt lgkmcnt(0)
	s_add_u32 s4, s74, 0xfff00080
	s_addc_u32 s5, s75, -1
	s_add_i32 s6, 0, 0x10000
	s_cmp_eq_u32 s95, 60
	s_cselect_b32 vcc_hi, s18, s5
	s_cselect_b32 vcc_lo, s21, s4
	s_cselect_b32 s79, s27, s94
	s_cselect_b32 s78, s69, s71
	s_add_i32 s7, 0, 0x14000
	v_add_u32_e32 v128, s6, v205
	v_add_u32_e32 v160, s7, v205
	ds_read_b128 v[112:115], v128
	ds_read_b128 v[116:119], v128 offset:1024
	ds_read_b128 v[124:127], v128 offset:2048
	ds_read_b128 v[128:131], v128 offset:3072
	ds_read_b128 v[148:151], v160
	ds_read_b128 v[152:155], v160 offset:1024
	ds_read_b128 v[156:159], v160 offset:2048
	ds_read_b128 v[160:163], v160 offset:3072
	s_add_i32 s44, s91, 0
	v_lshl_add_u64 v[194:195], s[74:75], 0, v[98:99]
	s_add_i32 m0, s44, 0xc000
	ds_read_b128 v[164:167], v207
	ds_read_b128 v[168:171], v207 offset:1024
	ds_read_b128 v[178:181], v207 offset:2048
	ds_read_b128 v[182:185], v207 offset:3072
	ds_read_b128 v[186:189], v207 offset:4096
	ds_read_b128 v[190:193], v207 offset:5120
	ds_read_b128 v[200:203], v207 offset:6144
	ds_read_b128 v[208:211], v207 offset:7168
	global_load_lds_dwordx4 v[194:195], off
	v_lshl_add_u64 v[194:195], s[74:75], 0, v[174:175]
	s_add_i32 m0, s44, 0xe000
	s_nop 0
	global_load_lds_dwordx4 v[194:195], off
	s_cmp_eq_u32 s100, 1
	s_cbranch_scc1 .Lmy_sk9_pk
	s_waitcnt vmcnt(8)
.Lmy_sk9_pk:
	s_waitcnt lgkmcnt(0)
	s_setprio 1
	s_barrier
	v_mfma_f32_16x16x32_bf16 v[144:147], v[112:115], v[164:167], 0
	v_mfma_f32_16x16x32_bf16 v[140:143], v[124:127], v[164:167], 0
	v_mfma_f32_16x16x32_bf16 v[120:123], v[112:115], v[178:181], 0
	v_mfma_f32_16x16x32_bf16 v[108:111], v[124:127], v[178:181], 0
	v_mfma_f32_16x16x32_bf16 v[94:97], v[112:115], v[186:189], 0
	v_mfma_f32_16x16x32_bf16 v[90:93], v[124:127], v[186:189], 0
	v_mfma_f32_16x16x32_bf16 v[78:81], v[112:115], v[200:203], 0
	v_mfma_f32_16x16x32_bf16 v[74:77], v[124:127], v[200:203], 0
	v_mfma_f32_16x16x32_bf16 v[144:147], v[116:119], v[168:171], v[144:147]
	v_mfma_f32_16x16x32_bf16 v[140:143], v[128:131], v[168:171], v[140:143]
	v_mfma_f32_16x16x32_bf16 v[120:123], v[116:119], v[182:185], v[120:123]
	v_mfma_f32_16x16x32_bf16 v[108:111], v[128:131], v[182:185], v[108:111]
	v_mfma_f32_16x16x32_bf16 v[94:97], v[116:119], v[190:193], v[94:97]
	v_mfma_f32_16x16x32_bf16 v[90:93], v[128:131], v[190:193], v[90:93]
	v_mfma_f32_16x16x32_bf16 v[78:81], v[116:119], v[208:211], v[78:81]
	v_mfma_f32_16x16x32_bf16 v[74:77], v[128:131], v[208:211], v[74:77]
	s_setprio 0
	s_setprio 1
	v_mfma_f32_16x16x32_bf16 v[136:139], v[148:151], v[164:167], 0
	v_mfma_f32_16x16x32_bf16 v[132:135], v[156:159], v[164:167], 0
	v_mfma_f32_16x16x32_bf16 v[104:107], v[148:151], v[178:181], 0
	v_mfma_f32_16x16x32_bf16 v[100:103], v[156:159], v[178:181], 0
	v_mfma_f32_16x16x32_bf16 v[86:89], v[148:151], v[186:189], 0
	v_mfma_f32_16x16x32_bf16 v[82:85], v[156:159], v[186:189], 0
	v_mfma_f32_16x16x32_bf16 v[70:73], v[148:151], v[200:203], 0
	v_mfma_f32_16x16x32_bf16 v[66:69], v[156:159], v[200:203], 0
	v_mfma_f32_16x16x32_bf16 v[136:139], v[152:155], v[168:171], v[136:139]
	v_mfma_f32_16x16x32_bf16 v[132:135], v[160:163], v[168:171], v[132:135]
	v_mfma_f32_16x16x32_bf16 v[104:107], v[152:155], v[182:185], v[104:107]
	v_mfma_f32_16x16x32_bf16 v[100:103], v[160:163], v[182:185], v[100:103]
	v_mfma_f32_16x16x32_bf16 v[86:89], v[152:155], v[190:193], v[86:89]
	v_mfma_f32_16x16x32_bf16 v[82:85], v[160:163], v[190:193], v[82:85]
	v_mfma_f32_16x16x32_bf16 v[70:73], v[152:155], v[208:211], v[70:73]
	v_mfma_f32_16x16x32_bf16 v[66:69], v[160:163], v[208:211], v[66:69]
	s_setprio 0
	s_barrier
	s_add_i32 s4, s6, s91
	v_lshl_add_u64 v[194:195], s[78:79], 0, v[172:173]
	s_mov_b32 m0, s4
	ds_read_b128 v[164:167], v207 offset:16384
	ds_read_b128 v[168:171], v207 offset:17408
	ds_read_b128 v[178:181], v207 offset:18432
	ds_read_b128 v[182:185], v207 offset:19456
	ds_read_b128 v[186:189], v207 offset:20480
	ds_read_b128 v[190:193], v207 offset:21504
	ds_read_b128 v[200:203], v207 offset:22528
	ds_read_b128 v[208:211], v207 offset:23552
	global_load_lds_dwordx4 v[194:195], off
	s_add_i32 m0, s4, 0x2000
	s_add_u32 s4, s78, 0x100000
	v_lshl_add_u64 v[212:213], s[78:79], 0, v[176:177]
	s_addc_u32 s5, s79, 0
	s_add_i32 s6, s7, s91
	global_load_lds_dwordx4 v[212:213], off
	v_lshl_add_u64 v[214:215], s[4:5], 0, v[172:173]
	s_mov_b32 m0, s6
	v_lshl_add_u64 v[216:217], vcc, 0, v[174:175]
	global_load_lds_dwordx4 v[214:215], off
	v_lshl_add_u64 v[214:215], s[4:5], 0, v[176:177]
	s_add_i32 m0, s6, 0x2000
	s_nop 0
	global_load_lds_dwordx4 v[214:215], off
	v_lshl_add_u64 v[214:215], vcc, 0, v[98:99]
	s_mov_b32 m0, s44
	s_nop 0
	global_load_lds_dwordx4 v[214:215], off
	s_add_i32 m0, s44, 0x2000
	s_nop 0
	global_load_lds_dwordx4 v[216:217], off
	s_cmp_eq_u32 s100, 1
	s_cbranch_scc1 .Lmy_sk10_pk
	s_waitcnt vmcnt(8)
.Lmy_sk10_pk:
	s_waitcnt lgkmcnt(0)
	s_setprio 1
	s_barrier
	v_mfma_f32_16x16x32_bf16 v[62:65], v[112:115], v[164:167], 0
	v_mfma_f32_16x16x32_bf16 v[58:61], v[124:127], v[164:167], 0
	v_mfma_f32_16x16x32_bf16 v[46:49], v[112:115], v[178:181], 0
	v_mfma_f32_16x16x32_bf16 v[42:45], v[124:127], v[178:181], 0
	v_mfma_f32_16x16x32_bf16 v[30:33], v[112:115], v[186:189], 0
	v_mfma_f32_16x16x32_bf16 v[26:29], v[124:127], v[186:189], 0
	v_mfma_f32_16x16x32_bf16 v[14:17], v[112:115], v[200:203], 0
	v_mfma_f32_16x16x32_bf16 v[10:13], v[124:127], v[200:203], 0
	v_mfma_f32_16x16x32_bf16 v[62:65], v[116:119], v[168:171], v[62:65]
	v_mfma_f32_16x16x32_bf16 v[58:61], v[128:131], v[168:171], v[58:61]
	v_mfma_f32_16x16x32_bf16 v[46:49], v[116:119], v[182:185], v[46:49]
	v_mfma_f32_16x16x32_bf16 v[42:45], v[128:131], v[182:185], v[42:45]
	v_mfma_f32_16x16x32_bf16 v[30:33], v[116:119], v[190:193], v[30:33]
	v_mfma_f32_16x16x32_bf16 v[26:29], v[128:131], v[190:193], v[26:29]
	v_mfma_f32_16x16x32_bf16 v[14:17], v[116:119], v[208:211], v[14:17]
	v_mfma_f32_16x16x32_bf16 v[10:13], v[128:131], v[208:211], v[10:13]
	s_setprio 0
	s_setprio 1
	v_mfma_f32_16x16x32_bf16 v[54:57], v[148:151], v[164:167], 0
	v_mfma_f32_16x16x32_bf16 v[50:53], v[156:159], v[164:167], 0
	v_mfma_f32_16x16x32_bf16 v[38:41], v[148:151], v[178:181], 0
	v_mfma_f32_16x16x32_bf16 v[34:37], v[156:159], v[178:181], 0
	v_mfma_f32_16x16x32_bf16 v[22:25], v[148:151], v[186:189], 0
	v_mfma_f32_16x16x32_bf16 v[18:21], v[156:159], v[186:189], 0
	v_mfma_f32_16x16x32_bf16 v[6:9], v[148:151], v[200:203], 0
	v_mfma_f32_16x16x32_bf16 v[2:5], v[156:159], v[200:203], 0
	v_mfma_f32_16x16x32_bf16 v[54:57], v[152:155], v[168:171], v[54:57]
	v_mfma_f32_16x16x32_bf16 v[50:53], v[160:163], v[168:171], v[50:53]
	v_mfma_f32_16x16x32_bf16 v[38:41], v[152:155], v[182:185], v[38:41]
	v_mfma_f32_16x16x32_bf16 v[34:37], v[160:163], v[182:185], v[34:37]
	v_mfma_f32_16x16x32_bf16 v[22:25], v[152:155], v[190:193], v[22:25]
	v_mfma_f32_16x16x32_bf16 v[18:21], v[160:163], v[190:193], v[18:21]
	v_mfma_f32_16x16x32_bf16 v[6:9], v[152:155], v[208:211], v[6:9]
	v_mfma_f32_16x16x32_bf16 v[2:5], v[160:163], v[208:211], v[2:5]
	s_setprio 0
	s_barrier
	s_add_i32 s6, 0, 0x18000
	s_add_i32 s7, 0, 0x1c000
	v_add_u32_e32 v128, s6, v205
	v_add_u32_e32 v160, s7, v205
	ds_read_b128 v[112:115], v128
	ds_read_b128 v[116:119], v128 offset:1024
	ds_read_b128 v[124:127], v128 offset:2048
	ds_read_b128 v[128:131], v128 offset:3072
	ds_read_b128 v[148:151], v160
	ds_read_b128 v[152:155], v160 offset:1024
	ds_read_b128 v[156:159], v160 offset:2048
	ds_read_b128 v[160:163], v160 offset:3072
	s_add_u32 s4, vcc_lo, 0x100000
	s_addc_u32 s5, vcc_hi, 0
	v_lshl_add_u64 v[218:219], s[4:5], 0, v[98:99]
	s_add_i32 m0, s44, 0x4000
	ds_read_b128 v[164:167], v207 offset:32768
	ds_read_b128 v[168:171], v207 offset:33792
	ds_read_b128 v[178:181], v207 offset:34816
	ds_read_b128 v[182:185], v207 offset:35840
	ds_read_b128 v[186:189], v207 offset:36864
	ds_read_b128 v[190:193], v207 offset:37888
	ds_read_b128 v[200:203], v207 offset:38912
	ds_read_b128 v[208:211], v207 offset:39936
	global_load_lds_dwordx4 v[218:219], off
	v_lshl_add_u64 v[218:219], s[4:5], 0, v[174:175]
	s_add_i32 m0, s44, 0x6000
	s_nop 0
	global_load_lds_dwordx4 v[218:219], off
	s_waitcnt vmcnt(8)
	s_waitcnt lgkmcnt(0)
	s_setprio 1
	s_barrier
	v_mfma_f32_16x16x32_bf16 v[144:147], v[112:115], v[164:167], v[144:147]
	v_mfma_f32_16x16x32_bf16 v[140:143], v[124:127], v[164:167], v[140:143]
	v_mfma_f32_16x16x32_bf16 v[120:123], v[112:115], v[178:181], v[120:123]
	v_mfma_f32_16x16x32_bf16 v[108:111], v[124:127], v[178:181], v[108:111]
	v_mfma_f32_16x16x32_bf16 v[94:97], v[112:115], v[186:189], v[94:97]
	v_mfma_f32_16x16x32_bf16 v[90:93], v[124:127], v[186:189], v[90:93]
	v_mfma_f32_16x16x32_bf16 v[78:81], v[112:115], v[200:203], v[78:81]
	v_mfma_f32_16x16x32_bf16 v[74:77], v[124:127], v[200:203], v[74:77]
	v_mfma_f32_16x16x32_bf16 v[144:147], v[116:119], v[168:171], v[144:147]
	v_mfma_f32_16x16x32_bf16 v[140:143], v[128:131], v[168:171], v[140:143]
	v_mfma_f32_16x16x32_bf16 v[120:123], v[116:119], v[182:185], v[120:123]
	v_mfma_f32_16x16x32_bf16 v[108:111], v[128:131], v[182:185], v[108:111]
	v_mfma_f32_16x16x32_bf16 v[94:97], v[116:119], v[190:193], v[94:97]
	v_mfma_f32_16x16x32_bf16 v[90:93], v[128:131], v[190:193], v[90:93]
	v_mfma_f32_16x16x32_bf16 v[78:81], v[116:119], v[208:211], v[78:81]
	v_mfma_f32_16x16x32_bf16 v[74:77], v[128:131], v[208:211], v[74:77]
	s_setprio 0
	s_setprio 1
	v_mfma_f32_16x16x32_bf16 v[136:139], v[148:151], v[164:167], v[136:139]
	v_mfma_f32_16x16x32_bf16 v[132:135], v[156:159], v[164:167], v[132:135]
	v_mfma_f32_16x16x32_bf16 v[104:107], v[148:151], v[178:181], v[104:107]
	v_mfma_f32_16x16x32_bf16 v[100:103], v[156:159], v[178:181], v[100:103]
	v_mfma_f32_16x16x32_bf16 v[86:89], v[148:151], v[186:189], v[86:89]
	v_mfma_f32_16x16x32_bf16 v[82:85], v[156:159], v[186:189], v[82:85]
	v_mfma_f32_16x16x32_bf16 v[70:73], v[148:151], v[200:203], v[70:73]
	v_mfma_f32_16x16x32_bf16 v[66:69], v[156:159], v[200:203], v[66:69]
	v_mfma_f32_16x16x32_bf16 v[136:139], v[152:155], v[168:171], v[136:139]
	v_mfma_f32_16x16x32_bf16 v[132:135], v[160:163], v[168:171], v[132:135]
	v_mfma_f32_16x16x32_bf16 v[104:107], v[152:155], v[182:185], v[104:107]
	v_mfma_f32_16x16x32_bf16 v[100:103], v[160:163], v[182:185], v[100:103]
	v_mfma_f32_16x16x32_bf16 v[86:89], v[152:155], v[190:193], v[86:89]
	v_mfma_f32_16x16x32_bf16 v[82:85], v[160:163], v[190:193], v[82:85]
	v_mfma_f32_16x16x32_bf16 v[70:73], v[152:155], v[208:211], v[70:73]
	v_mfma_f32_16x16x32_bf16 v[66:69], v[160:163], v[208:211], v[66:69]
	s_setprio 0
	s_barrier
	s_add_i32 s4, s6, s91
	v_lshl_add_u64 v[194:195], v[194:195], 0, s[42:43]
	s_mov_b32 m0, s4
	ds_read_b128 v[164:167], v207 offset:49152
	ds_read_b128 v[168:171], v207 offset:50176
	ds_read_b128 v[178:181], v207 offset:51200
	ds_read_b128 v[182:185], v207 offset:52224
	ds_read_b128 v[186:189], v207 offset:53248
	ds_read_b128 v[190:193], v207 offset:54272
	ds_read_b128 v[200:203], v207 offset:55296
	ds_read_b128 v[208:211], v207 offset:56320
	global_load_lds_dwordx4 v[194:195], off
	s_add_i32 m0, s4, 0x2000
	s_add_u32 s4, s78, 0x100080
	v_lshl_add_u64 v[194:195], v[212:213], 0, s[42:43]
	s_addc_u32 s5, s79, 0
	s_add_i32 s6, s7, s91
	global_load_lds_dwordx4 v[194:195], off
	v_lshl_add_u64 v[194:195], s[4:5], 0, v[172:173]
	s_mov_b32 m0, s6
	s_nop 0
	global_load_lds_dwordx4 v[194:195], off
	v_lshl_add_u64 v[194:195], s[4:5], 0, v[176:177]
	s_add_i32 m0, s6, 0x2000
	s_nop 0
	global_load_lds_dwordx4 v[194:195], off
	v_lshl_add_u64 v[194:195], v[214:215], 0, s[42:43]
	s_add_i32 m0, s44, 0x8000
	s_nop 0
	global_load_lds_dwordx4 v[194:195], off
	v_lshl_add_u64 v[194:195], v[216:217], 0, s[42:43]
	s_add_i32 m0, s44, 0xa000
	s_nop 0
	global_load_lds_dwordx4 v[194:195], off
	s_waitcnt vmcnt(8)
	s_waitcnt lgkmcnt(0)
	s_setprio 1
	s_barrier
	v_mfma_f32_16x16x32_bf16 v[62:65], v[112:115], v[164:167], v[62:65]
	v_mfma_f32_16x16x32_bf16 v[58:61], v[124:127], v[164:167], v[58:61]
	v_mfma_f32_16x16x32_bf16 v[46:49], v[112:115], v[178:181], v[46:49]
	v_mfma_f32_16x16x32_bf16 v[42:45], v[124:127], v[178:181], v[42:45]
	v_mfma_f32_16x16x32_bf16 v[30:33], v[112:115], v[186:189], v[30:33]
	v_mfma_f32_16x16x32_bf16 v[26:29], v[124:127], v[186:189], v[26:29]
	v_mfma_f32_16x16x32_bf16 v[14:17], v[112:115], v[200:203], v[14:17]
	v_mfma_f32_16x16x32_bf16 v[10:13], v[124:127], v[200:203], v[10:13]
	v_mfma_f32_16x16x32_bf16 v[62:65], v[116:119], v[168:171], v[62:65]
	v_mfma_f32_16x16x32_bf16 v[58:61], v[128:131], v[168:171], v[58:61]
	v_mfma_f32_16x16x32_bf16 v[46:49], v[116:119], v[182:185], v[46:49]
	v_mfma_f32_16x16x32_bf16 v[42:45], v[128:131], v[182:185], v[42:45]
	v_mfma_f32_16x16x32_bf16 v[30:33], v[116:119], v[190:193], v[30:33]
	v_mfma_f32_16x16x32_bf16 v[26:29], v[128:131], v[190:193], v[26:29]
	v_mfma_f32_16x16x32_bf16 v[14:17], v[116:119], v[208:211], v[14:17]
	v_mfma_f32_16x16x32_bf16 v[10:13], v[128:131], v[208:211], v[10:13]
	s_setprio 0
	s_setprio 1
	v_mfma_f32_16x16x32_bf16 v[54:57], v[148:151], v[164:167], v[54:57]
	v_mfma_f32_16x16x32_bf16 v[50:53], v[156:159], v[164:167], v[50:53]
	v_mfma_f32_16x16x32_bf16 v[38:41], v[148:151], v[178:181], v[38:41]
	v_mfma_f32_16x16x32_bf16 v[34:37], v[156:159], v[178:181], v[34:37]
	v_mfma_f32_16x16x32_bf16 v[22:25], v[148:151], v[186:189], v[22:25]
	v_mfma_f32_16x16x32_bf16 v[18:21], v[156:159], v[186:189], v[18:21]
	v_mfma_f32_16x16x32_bf16 v[6:9], v[148:151], v[200:203], v[6:9]
	v_mfma_f32_16x16x32_bf16 v[2:5], v[156:159], v[200:203], v[2:5]
	v_mfma_f32_16x16x32_bf16 v[54:57], v[152:155], v[168:171], v[54:57]
	v_mfma_f32_16x16x32_bf16 v[50:53], v[160:163], v[168:171], v[50:53]
	v_mfma_f32_16x16x32_bf16 v[38:41], v[152:155], v[182:185], v[38:41]
	v_mfma_f32_16x16x32_bf16 v[34:37], v[160:163], v[182:185], v[34:37]
	v_mfma_f32_16x16x32_bf16 v[22:25], v[152:155], v[190:193], v[22:25]
	v_mfma_f32_16x16x32_bf16 v[18:21], v[160:163], v[190:193], v[18:21]
	v_mfma_f32_16x16x32_bf16 v[6:9], v[152:155], v[208:211], v[6:9]
	v_mfma_f32_16x16x32_bf16 v[2:5], v[160:163], v[208:211], v[2:5]
	s_setprio 0
	s_barrier
	s_mov_b32 s100, 0
	s_add_i32 s95, s95, 2
	s_add_u32 s74, s74, 0x100
	s_addc_u32 s75, s75, 0
	s_add_u32 s71, s71, 0x100
	s_addc_u32 s94, s94, 0
	s_cmp_gt_u32 s95, 61

.LBB0_1171:
	s_ashr_i32 s27, s26, 31
	s_lshl_b64 s[4:5], s[26:27], 21
	s_add_u32 s40, s24, s4
	s_addc_u32 s41, s25, s5
	s_and_b64 s[4:5], s[30:31], exec
	s_cselect_b32 s18, s41, s71
	s_cselect_b32 s27, s40, s70
	s_ashr_i32 s15, s14, 31
	s_lshl_b64 s[4:5], s[14:15], 21
	s_add_u32 s20, s77, s4
	s_addc_u32 s21, s88, s5
	s_and_b64 s[4:5], s[30:31], exec
	s_cselect_b32 s15, s21, s75
	s_cselect_b32 s57, s20, s74
	s_add_u32 s70, s70, 0x100080
	s_addc_u32 s71, s71, 0
	s_add_u32 s69, s74, 0x100
	s_addc_u32 s94, s75, 0
	s_mov_b32 s95, -2
	s_waitcnt lgkmcnt(0)
	s_add_u32 s4, s70, 0xfff00080
	s_addc_u32 s5, s71, -1
	s_add_i32 s6, 0, 0x10000
	s_cmp_eq_u32 s95, 60
	s_cselect_b32 s79, s18, s5
	s_cselect_b32 s78, s27, s4
	s_cselect_b32 s75, s15, s94
	s_cselect_b32 s74, s57, s69
	s_add_i32 s7, 0, 0x14000
	v_add_u32_e32 v104, s6, v239
	v_add_u32_e32 v128, s7, v239
	ds_read_b128 v[90:93], v104
	ds_read_b128 v[94:97], v104 offset:1024
	ds_read_b128 v[100:103], v104 offset:2048
	ds_read_b128 v[104:107], v104 offset:3072
	ds_read_b128 v[108:111], v128
	ds_read_b128 v[112:115], v128 offset:1024
	ds_read_b128 v[120:123], v128 offset:2048
	ds_read_b128 v[128:131], v128 offset:3072
	s_add_i32 s44, s91, 0
	v_lshl_add_u64 v[200:201], s[70:71], 0, v[98:99]
	s_add_i32 m0, s44, 0xc000
	ds_read_b128 v[164:167], v241
	ds_read_b128 v[168:171], v241 offset:1024
	ds_read_b128 v[172:175], v241 offset:2048
	ds_read_b128 v[176:179], v241 offset:3072
	ds_read_b128 v[180:183], v241 offset:4096
	ds_read_b128 v[184:187], v241 offset:5120
	ds_read_b128 v[188:191], v241 offset:6144
	ds_read_b128 v[192:195], v241 offset:7168
	global_load_lds_dwordx4 v[200:201], off
	v_lshl_add_u64 v[200:201], s[70:71], 0, v[206:207]
	s_add_i32 m0, s44, 0xe000
	s_nop 0
	global_load_lds_dwordx4 v[200:201], off
	s_cmp_eq_u32 s100, 1
	s_cbranch_scc1 .Lmy_sk11_pk
	s_waitcnt vmcnt(8)
.Lmy_sk11_pk:
	s_waitcnt lgkmcnt(0)
	s_setprio 1
	s_barrier
	v_mfma_f32_16x16x32_bf16 v[160:163], v[90:93], v[164:167], 0
	v_mfma_f32_16x16x32_bf16 v[156:159], v[100:103], v[164:167], 0
	v_mfma_f32_16x16x32_bf16 v[144:147], v[90:93], v[172:175], 0
	v_mfma_f32_16x16x32_bf16 v[140:143], v[100:103], v[172:175], 0
	v_mfma_f32_16x16x32_bf16 v[124:127], v[90:93], v[180:183], 0
	v_mfma_f32_16x16x32_bf16 v[116:119], v[100:103], v[180:183], 0
	v_mfma_f32_16x16x32_bf16 v[78:81], v[90:93], v[188:191], 0
	v_mfma_f32_16x16x32_bf16 v[74:77], v[100:103], v[188:191], 0
	v_mfma_f32_16x16x32_bf16 v[160:163], v[94:97], v[168:171], v[160:163]
	v_mfma_f32_16x16x32_bf16 v[156:159], v[104:107], v[168:171], v[156:159]
	v_mfma_f32_16x16x32_bf16 v[144:147], v[94:97], v[176:179], v[144:147]
	v_mfma_f32_16x16x32_bf16 v[140:143], v[104:107], v[176:179], v[140:143]
	v_mfma_f32_16x16x32_bf16 v[124:127], v[94:97], v[184:187], v[124:127]
	v_mfma_f32_16x16x32_bf16 v[116:119], v[104:107], v[184:187], v[116:119]
	v_mfma_f32_16x16x32_bf16 v[78:81], v[94:97], v[192:195], v[78:81]
	v_mfma_f32_16x16x32_bf16 v[74:77], v[104:107], v[192:195], v[74:77]
	s_setprio 0
	s_setprio 1
	v_mfma_f32_16x16x32_bf16 v[152:155], v[108:111], v[164:167], 0
	v_mfma_f32_16x16x32_bf16 v[148:151], v[120:123], v[164:167], 0
	v_mfma_f32_16x16x32_bf16 v[136:139], v[108:111], v[172:175], 0
	v_mfma_f32_16x16x32_bf16 v[132:135], v[120:123], v[172:175], 0
	v_mfma_f32_16x16x32_bf16 v[86:89], v[108:111], v[180:183], 0
	v_mfma_f32_16x16x32_bf16 v[82:85], v[120:123], v[180:183], 0
	v_mfma_f32_16x16x32_bf16 v[70:73], v[108:111], v[188:191], 0
	v_mfma_f32_16x16x32_bf16 v[66:69], v[120:123], v[188:191], 0
	v_mfma_f32_16x16x32_bf16 v[152:155], v[112:115], v[168:171], v[152:155]
	v_mfma_f32_16x16x32_bf16 v[148:151], v[128:131], v[168:171], v[148:151]
	v_mfma_f32_16x16x32_bf16 v[136:139], v[112:115], v[176:179], v[136:139]
	v_mfma_f32_16x16x32_bf16 v[132:135], v[128:131], v[176:179], v[132:135]
	v_mfma_f32_16x16x32_bf16 v[86:89], v[112:115], v[184:187], v[86:89]
	v_mfma_f32_16x16x32_bf16 v[82:85], v[128:131], v[184:187], v[82:85]
	v_mfma_f32_16x16x32_bf16 v[70:73], v[112:115], v[192:195], v[70:73]
	v_mfma_f32_16x16x32_bf16 v[66:69], v[128:131], v[192:195], v[66:69]
	s_setprio 0
	s_barrier
	s_add_i32 s4, s6, s91
	v_lshl_add_u64 v[200:201], s[74:75], 0, v[204:205]
	s_mov_b32 m0, s4
	ds_read_b128 v[164:167], v241 offset:16384
	ds_read_b128 v[168:171], v241 offset:17408
	ds_read_b128 v[172:175], v241 offset:18432
	ds_read_b128 v[176:179], v241 offset:19456
	ds_read_b128 v[180:183], v241 offset:20480
	ds_read_b128 v[184:187], v241 offset:21504
	ds_read_b128 v[188:191], v241 offset:22528
	ds_read_b128 v[192:195], v241 offset:23552
	global_load_lds_dwordx4 v[200:201], off
	s_add_i32 m0, s4, 0x2000
	s_add_u32 s4, s74, 0x100000
	v_lshl_add_u64 v[202:203], s[74:75], 0, v[208:209]
	s_addc_u32 s5, s75, 0
	s_add_i32 s6, s7, s91
	global_load_lds_dwordx4 v[202:203], off
	v_lshl_add_u64 v[210:211], s[4:5], 0, v[204:205]
	s_mov_b32 m0, s6
	v_lshl_add_u64 v[212:213], s[78:79], 0, v[206:207]
	global_load_lds_dwordx4 v[210:211], off
	v_lshl_add_u64 v[210:211], s[4:5], 0, v[208:209]
	s_add_i32 m0, s6, 0x2000
	s_nop 0
	global_load_lds_dwordx4 v[210:211], off
	v_lshl_add_u64 v[210:211], s[78:79], 0, v[98:99]
	s_mov_b32 m0, s44
	s_nop 0
	global_load_lds_dwordx4 v[210:211], off
	s_add_i32 m0, s44, 0x2000
	s_nop 0
	global_load_lds_dwordx4 v[212:213], off
	s_cmp_eq_u32 s100, 1
	s_cbranch_scc1 .Lmy_sk12_pk
	s_waitcnt vmcnt(8)
.Lmy_sk12_pk:
	s_waitcnt lgkmcnt(0)
	s_setprio 1
	s_barrier
	v_mfma_f32_16x16x32_bf16 v[62:65], v[90:93], v[164:167], 0
	v_mfma_f32_16x16x32_bf16 v[58:61], v[100:103], v[164:167], 0
	v_mfma_f32_16x16x32_bf16 v[46:49], v[90:93], v[172:175], 0
	v_mfma_f32_16x16x32_bf16 v[42:45], v[100:103], v[172:175], 0
	v_mfma_f32_16x16x32_bf16 v[30:33], v[90:93], v[180:183], 0
	v_mfma_f32_16x16x32_bf16 v[26:29], v[100:103], v[180:183], 0
	v_mfma_f32_16x16x32_bf16 v[14:17], v[90:93], v[188:191], 0
	v_mfma_f32_16x16x32_bf16 v[10:13], v[100:103], v[188:191], 0
	v_mfma_f32_16x16x32_bf16 v[62:65], v[94:97], v[168:171], v[62:65]
	v_mfma_f32_16x16x32_bf16 v[58:61], v[104:107], v[168:171], v[58:61]
	v_mfma_f32_16x16x32_bf16 v[46:49], v[94:97], v[176:179], v[46:49]
	v_mfma_f32_16x16x32_bf16 v[42:45], v[104:107], v[176:179], v[42:45]
	v_mfma_f32_16x16x32_bf16 v[30:33], v[94:97], v[184:187], v[30:33]
	v_mfma_f32_16x16x32_bf16 v[26:29], v[104:107], v[184:187], v[26:29]
	v_mfma_f32_16x16x32_bf16 v[14:17], v[94:97], v[192:195], v[14:17]
	v_mfma_f32_16x16x32_bf16 v[10:13], v[104:107], v[192:195], v[10:13]
	s_setprio 0
	s_setprio 1
	v_mfma_f32_16x16x32_bf16 v[54:57], v[108:111], v[164:167], 0
	v_mfma_f32_16x16x32_bf16 v[50:53], v[120:123], v[164:167], 0
	v_mfma_f32_16x16x32_bf16 v[38:41], v[108:111], v[172:175], 0
	v_mfma_f32_16x16x32_bf16 v[34:37], v[120:123], v[172:175], 0
	v_mfma_f32_16x16x32_bf16 v[22:25], v[108:111], v[180:183], 0
	v_mfma_f32_16x16x32_bf16 v[18:21], v[120:123], v[180:183], 0
	v_mfma_f32_16x16x32_bf16 v[6:9], v[108:111], v[188:191], 0
	v_mfma_f32_16x16x32_bf16 v[2:5], v[120:123], v[188:191], 0
	v_mfma_f32_16x16x32_bf16 v[54:57], v[112:115], v[168:171], v[54:57]
	v_mfma_f32_16x16x32_bf16 v[50:53], v[128:131], v[168:171], v[50:53]
	v_mfma_f32_16x16x32_bf16 v[38:41], v[112:115], v[176:179], v[38:41]
	v_mfma_f32_16x16x32_bf16 v[34:37], v[128:131], v[176:179], v[34:37]
	v_mfma_f32_16x16x32_bf16 v[22:25], v[112:115], v[184:187], v[22:25]
	v_mfma_f32_16x16x32_bf16 v[18:21], v[128:131], v[184:187], v[18:21]
	v_mfma_f32_16x16x32_bf16 v[6:9], v[112:115], v[192:195], v[6:9]
	v_mfma_f32_16x16x32_bf16 v[2:5], v[128:131], v[192:195], v[2:5]
	s_setprio 0
	s_barrier
	s_add_i32 s6, 0, 0x18000
	s_add_i32 s7, 0, 0x1c000
	v_add_u32_e32 v104, s6, v239
	v_add_u32_e32 v128, s7, v239
	ds_read_b128 v[90:93], v104
	ds_read_b128 v[94:97], v104 offset:1024
	ds_read_b128 v[100:103], v104 offset:2048
	ds_read_b128 v[104:107], v104 offset:3072
	ds_read_b128 v[108:111], v128
	ds_read_b128 v[112:115], v128 offset:1024
	ds_read_b128 v[120:123], v128 offset:2048
	ds_read_b128 v[128:131], v128 offset:3072
	s_add_u32 s4, s78, 0x100000
	s_addc_u32 s5, s79, 0
	v_lshl_add_u64 v[214:215], s[4:5], 0, v[98:99]
	s_add_i32 m0, s44, 0x4000
	ds_read_b128 v[164:167], v241 offset:32768
	ds_read_b128 v[168:171], v241 offset:33792
	ds_read_b128 v[172:175], v241 offset:34816
	ds_read_b128 v[176:179], v241 offset:35840
	ds_read_b128 v[180:183], v241 offset:36864
	ds_read_b128 v[184:187], v241 offset:37888
	ds_read_b128 v[188:191], v241 offset:38912
	ds_read_b128 v[192:195], v241 offset:39936
	global_load_lds_dwordx4 v[214:215], off
	v_lshl_add_u64 v[214:215], s[4:5], 0, v[206:207]
	s_add_i32 m0, s44, 0x6000
	s_nop 0
	global_load_lds_dwordx4 v[214:215], off
	s_waitcnt vmcnt(8)
	s_waitcnt lgkmcnt(0)
	s_setprio 1
	s_barrier
	v_mfma_f32_16x16x32_bf16 v[160:163], v[90:93], v[164:167], v[160:163]
	v_mfma_f32_16x16x32_bf16 v[156:159], v[100:103], v[164:167], v[156:159]
	v_mfma_f32_16x16x32_bf16 v[144:147], v[90:93], v[172:175], v[144:147]
	v_mfma_f32_16x16x32_bf16 v[140:143], v[100:103], v[172:175], v[140:143]
	v_mfma_f32_16x16x32_bf16 v[124:127], v[90:93], v[180:183], v[124:127]
	v_mfma_f32_16x16x32_bf16 v[116:119], v[100:103], v[180:183], v[116:119]
	v_mfma_f32_16x16x32_bf16 v[78:81], v[90:93], v[188:191], v[78:81]
	v_mfma_f32_16x16x32_bf16 v[74:77], v[100:103], v[188:191], v[74:77]
	v_mfma_f32_16x16x32_bf16 v[160:163], v[94:97], v[168:171], v[160:163]
	v_mfma_f32_16x16x32_bf16 v[156:159], v[104:107], v[168:171], v[156:159]
	v_mfma_f32_16x16x32_bf16 v[144:147], v[94:97], v[176:179], v[144:147]
	v_mfma_f32_16x16x32_bf16 v[140:143], v[104:107], v[176:179], v[140:143]
	v_mfma_f32_16x16x32_bf16 v[124:127], v[94:97], v[184:187], v[124:127]
	v_mfma_f32_16x16x32_bf16 v[116:119], v[104:107], v[184:187], v[116:119]
	v_mfma_f32_16x16x32_bf16 v[78:81], v[94:97], v[192:195], v[78:81]
	v_mfma_f32_16x16x32_bf16 v[74:77], v[104:107], v[192:195], v[74:77]
	s_setprio 0
	s_setprio 1
	v_mfma_f32_16x16x32_bf16 v[152:155], v[108:111], v[164:167], v[152:155]
	v_mfma_f32_16x16x32_bf16 v[148:151], v[120:123], v[164:167], v[148:151]
	v_mfma_f32_16x16x32_bf16 v[136:139], v[108:111], v[172:175], v[136:139]
	v_mfma_f32_16x16x32_bf16 v[132:135], v[120:123], v[172:175], v[132:135]
	v_mfma_f32_16x16x32_bf16 v[86:89], v[108:111], v[180:183], v[86:89]
	v_mfma_f32_16x16x32_bf16 v[82:85], v[120:123], v[180:183], v[82:85]
	v_mfma_f32_16x16x32_bf16 v[70:73], v[108:111], v[188:191], v[70:73]
	v_mfma_f32_16x16x32_bf16 v[66:69], v[120:123], v[188:191], v[66:69]
	v_mfma_f32_16x16x32_bf16 v[152:155], v[112:115], v[168:171], v[152:155]
	v_mfma_f32_16x16x32_bf16 v[148:151], v[128:131], v[168:171], v[148:151]
	v_mfma_f32_16x16x32_bf16 v[136:139], v[112:115], v[176:179], v[136:139]
	v_mfma_f32_16x16x32_bf16 v[132:135], v[128:131], v[176:179], v[132:135]
	v_mfma_f32_16x16x32_bf16 v[86:89], v[112:115], v[184:187], v[86:89]
	v_mfma_f32_16x16x32_bf16 v[82:85], v[128:131], v[184:187], v[82:85]
	v_mfma_f32_16x16x32_bf16 v[70:73], v[112:115], v[192:195], v[70:73]
	v_mfma_f32_16x16x32_bf16 v[66:69], v[128:131], v[192:195], v[66:69]
	s_setprio 0
	s_barrier
	s_add_i32 s4, s6, s91
	v_lshl_add_u64 v[200:201], v[200:201], 0, s[42:43]
	s_mov_b32 m0, s4
	ds_read_b128 v[164:167], v241 offset:49152
	ds_read_b128 v[168:171], v241 offset:50176
	ds_read_b128 v[172:175], v241 offset:51200
	ds_read_b128 v[176:179], v241 offset:52224
	ds_read_b128 v[180:183], v241 offset:53248
	ds_read_b128 v[184:187], v241 offset:54272
	ds_read_b128 v[188:191], v241 offset:55296
	ds_read_b128 v[192:195], v241 offset:56320
	global_load_lds_dwordx4 v[200:201], off
	s_add_i32 m0, s4, 0x2000
	s_add_u32 s4, s74, 0x100080
	v_lshl_add_u64 v[200:201], v[202:203], 0, s[42:43]
	s_addc_u32 s5, s75, 0
	s_add_i32 s6, s7, s91
	global_load_lds_dwordx4 v[200:201], off
	v_lshl_add_u64 v[200:201], s[4:5], 0, v[204:205]
	s_mov_b32 m0, s6
	s_nop 0
	global_load_lds_dwordx4 v[200:201], off
	v_lshl_add_u64 v[200:201], s[4:5], 0, v[208:209]
	s_add_i32 m0, s6, 0x2000
	s_nop 0
	global_load_lds_dwordx4 v[200:201], off
	v_lshl_add_u64 v[200:201], v[210:211], 0, s[42:43]
	s_add_i32 m0, s44, 0x8000
	s_nop 0
	global_load_lds_dwordx4 v[200:201], off
	v_lshl_add_u64 v[200:201], v[212:213], 0, s[42:43]
	s_add_i32 m0, s44, 0xa000
	s_nop 0
	global_load_lds_dwordx4 v[200:201], off
	s_waitcnt vmcnt(8)
	s_waitcnt lgkmcnt(0)
	s_setprio 1
	s_barrier
	v_mfma_f32_16x16x32_bf16 v[62:65], v[90:93], v[164:167], v[62:65]
	v_mfma_f32_16x16x32_bf16 v[58:61], v[100:103], v[164:167], v[58:61]
	v_mfma_f32_16x16x32_bf16 v[46:49], v[90:93], v[172:175], v[46:49]
	v_mfma_f32_16x16x32_bf16 v[42:45], v[100:103], v[172:175], v[42:45]
	v_mfma_f32_16x16x32_bf16 v[30:33], v[90:93], v[180:183], v[30:33]
	v_mfma_f32_16x16x32_bf16 v[26:29], v[100:103], v[180:183], v[26:29]
	v_mfma_f32_16x16x32_bf16 v[14:17], v[90:93], v[188:191], v[14:17]
	v_mfma_f32_16x16x32_bf16 v[10:13], v[100:103], v[188:191], v[10:13]
	v_mfma_f32_16x16x32_bf16 v[62:65], v[94:97], v[168:171], v[62:65]
	v_mfma_f32_16x16x32_bf16 v[58:61], v[104:107], v[168:171], v[58:61]
	v_mfma_f32_16x16x32_bf16 v[46:49], v[94:97], v[176:179], v[46:49]
	v_mfma_f32_16x16x32_bf16 v[42:45], v[104:107], v[176:179], v[42:45]
	v_mfma_f32_16x16x32_bf16 v[30:33], v[94:97], v[184:187], v[30:33]
	v_mfma_f32_16x16x32_bf16 v[26:29], v[104:107], v[184:187], v[26:29]
	v_mfma_f32_16x16x32_bf16 v[14:17], v[94:97], v[192:195], v[14:17]
	v_mfma_f32_16x16x32_bf16 v[10:13], v[104:107], v[192:195], v[10:13]
	s_setprio 0
	s_setprio 1
	v_mfma_f32_16x16x32_bf16 v[54:57], v[108:111], v[164:167], v[54:57]
	v_mfma_f32_16x16x32_bf16 v[50:53], v[120:123], v[164:167], v[50:53]
	v_mfma_f32_16x16x32_bf16 v[38:41], v[108:111], v[172:175], v[38:41]
	v_mfma_f32_16x16x32_bf16 v[34:37], v[120:123], v[172:175], v[34:37]
	v_mfma_f32_16x16x32_bf16 v[22:25], v[108:111], v[180:183], v[22:25]
	v_mfma_f32_16x16x32_bf16 v[18:21], v[120:123], v[180:183], v[18:21]
	v_mfma_f32_16x16x32_bf16 v[6:9], v[108:111], v[188:191], v[6:9]
	v_mfma_f32_16x16x32_bf16 v[2:5], v[120:123], v[188:191], v[2:5]
	v_mfma_f32_16x16x32_bf16 v[54:57], v[112:115], v[168:171], v[54:57]
	v_mfma_f32_16x16x32_bf16 v[50:53], v[128:131], v[168:171], v[50:53]
	v_mfma_f32_16x16x32_bf16 v[38:41], v[112:115], v[176:179], v[38:41]
	v_mfma_f32_16x16x32_bf16 v[34:37], v[128:131], v[176:179], v[34:37]
	v_mfma_f32_16x16x32_bf16 v[22:25], v[112:115], v[184:187], v[22:25]
	v_mfma_f32_16x16x32_bf16 v[18:21], v[128:131], v[184:187], v[18:21]
	v_mfma_f32_16x16x32_bf16 v[6:9], v[112:115], v[192:195], v[6:9]
	v_mfma_f32_16x16x32_bf16 v[2:5], v[128:131], v[192:195], v[2:5]
	s_setprio 0
	s_barrier
	s_mov_b32 s100, 0
	s_add_i32 s95, s95, 2
	s_add_u32 s70, s70, 0x100
	s_addc_u32 s71, s71, 0
	s_add_u32 s69, s69, 0x100
	s_addc_u32 s94, s94, 0
	s_cmp_gt_u32 s95, 61
